# hand-written out-projection epilogue for layers 1-3: all residual-row loads issued ahead with counted waits, permlane row-sum, saddr stores
# baseline (speedup 1.0000x reference)
.LBB0_560:
	s_and_b64 vcc, exec, s[28:29]
	s_cbranch_vccnz .Lfo_entry
	s_lshr_b32 s14, s34, 3
	s_mulk_i32 s14, 0xc00
	s_ashr_i32 s15, s14, 31
	s_lshl_b64 s[14:15], s[14:15], 2
	s_add_u32 s16, s86, s14
	s_addc_u32 s17, s87, s15
	s_add_u32 s16, s16, 0x2000
	s_addc_u32 s17, s17, 0
	s_waitcnt lgkmcnt(0)
	v_lshl_add_u64 v[0:1], v[170:171], 2, s[16:17]
	global_load_dwordx4 v[142:145], v[0:1], off
	s_add_u32 s14, s88, s14
	s_addc_u32 s15, s89, s15
	s_add_u32 s86, s14, 0x1000
	v_mov_b32_e32 v186, 0
	v_cndmask_b32_e64 v0, 0, 1, s[40:41]
	s_addc_u32 s87, s15, 0
	v_cmp_ne_u32_e64 s[14:15], 1, v0
	s_andn2_b64 vcc, exec, s[40:41]
	v_mov_b32_e32 v190, 0
	v_mov_b32_e32 v191, v186
	v_mov_b32_e32 v192, 0
	v_mov_b32_e32 v193, 0
	s_cbranch_vccnz .LBB0_562
	v_lshlrev_b64 v[4:5], 2, v[170:171]
	v_lshl_add_u64 v[0:1], s[86:87], 0, v[4:5]
	global_load_dwordx4 v[0:3], v[0:1], off
	v_lshl_add_u64 v[4:5], s[26:27], 0, v[4:5]
	global_load_dwordx4 v[4:7], v[4:5], off
	s_waitcnt vmcnt(0)
	v_pk_add_f32 v[2:3], v[2:3], 1.0 op_sel_hi:[1,0]
	v_pk_add_f32 v[0:1], v[0:1], 1.0 op_sel_hi:[1,0]
	v_pk_mul_f32 v[192:193], v[6:7], v[2:3]
	v_pk_mul_f32 v[190:191], v[4:5], v[0:1]

.LBB0_720:
	s_branch .LBB0_1427
.Ltr_1429:
	s_branch .LBB0_1429
.Ltr_1427:
	s_branch .LBB0_1427
.Lfo_entry:
	s_lshr_b32 s14, s34, 3
	s_mul_i32 s14, s14, 0x3000
	s_add_u32 s16, s86, s14
	s_addc_u32 s17, s87, 0
	s_add_u32 s16, s16, 0x2000
	s_addc_u32 s17, s17, 0
	s_add_u32 s86, s88, s14
	s_addc_u32 s87, s89, 0
	s_add_u32 s86, s86, 0x1000
	s_addc_u32 s87, s87, 0
	v_lshl_add_u32 v171, v170, 1, v96
	v_lshl_add_u32 v171, v222, 11, v171
	v_lshlrev_b32_e32 v170, 2, v170
	s_lshl_b32 s14, s34, 8
	s_add_i32 s14, s14, s81
	s_lshl_b32 s12, s14, 11
	s_add_u32 s14, s2, s12
	s_addc_u32 s15, s3, 0
	s_add_u32 s78, s78, s12
	s_addc_u32 s79, s79, 0
	s_add_u32 s22, s78, 0x4000
	s_addc_u32 s23, s79, 0
	s_mov_b64 s[2:3], s[14:15]
	s_add_u32 s18, s14, 0x4000
	s_addc_u32 s19, s15, 0
	s_mov_b64 s[12:13], s[18:19]
	s_and_b64 vcc, exec, s[40:41]
	s_cbranch_vccz .Lfo_nong
	global_load_dwordx4 v[142:145], v170, s[16:17]
	global_load_dwordx4 v[150:153], v170, s[16:17] offset:16
	global_load_dwordx4 v[138:141], v170, s[16:17] offset:128
	global_load_dwordx4 v[146:149], v170, s[16:17] offset:144
	global_load_dwordx4 v[196:199], v171, s[14:15]
	global_load_dwordx4 v[200:203], v171, s[12:13]
	s_add_u32 s14, s14, 0x8000
	s_addc_u32 s15, s15, 0
	s_add_u32 s12, s12, 0x8000
	s_addc_u32 s13, s13, 0
	global_load_dwordx4 v[204:207], v171, s[14:15]
	global_load_dwordx4 v[234:237], v171, s[12:13]
	global_load_dwordx4 v[180:183], v170, s[86:87]
	global_load_dwordx4 v[184:187], v170, s[86:87] offset:16
	global_load_dwordx4 v[188:191], v170, s[86:87] offset:128
	global_load_dwordx4 v[192:195], v170, s[86:87] offset:144
	global_load_dwordx4 v[0:3], v170, s[26:27]
	global_load_dwordx4 v[4:7], v170, s[26:27] offset:16
	global_load_dwordx4 v[238:241], v170, s[26:27] offset:128
	global_load_dwordx4 v[242:245], v170, s[26:27] offset:144
	s_waitcnt vmcnt(0)
	v_pk_add_f32 v[182:183], v[182:183], 1.0 op_sel_hi:[1,0]
	v_pk_add_f32 v[180:181], v[180:181], 1.0 op_sel_hi:[1,0]
	v_pk_add_f32 v[186:187], v[186:187], 1.0 op_sel_hi:[1,0]
	v_pk_add_f32 v[184:185], v[184:185], 1.0 op_sel_hi:[1,0]
	v_pk_add_f32 v[190:191], v[190:191], 1.0 op_sel_hi:[1,0]
	v_pk_add_f32 v[188:189], v[188:189], 1.0 op_sel_hi:[1,0]
	v_pk_add_f32 v[194:195], v[194:195], 1.0 op_sel_hi:[1,0]
	v_pk_add_f32 v[192:193], v[192:193], 1.0 op_sel_hi:[1,0]
	v_pk_mul_f32 v[182:183], v[2:3], v[182:183]
	v_pk_mul_f32 v[180:181], v[0:1], v[180:181]
	v_pk_mul_f32 v[186:187], v[6:7], v[186:187]
	v_pk_mul_f32 v[184:185], v[4:5], v[184:185]
	v_pk_mul_f32 v[190:191], v[240:241], v[190:191]
	v_pk_mul_f32 v[188:189], v[238:239], v[188:189]
	v_pk_mul_f32 v[194:195], v[244:245], v[194:195]
	v_pk_mul_f32 v[192:193], v[242:243], v[192:193]
	s_add_u32 s14, s14, 0x8000
	s_addc_u32 s15, s15, 0
	s_add_u32 s12, s12, 0x8000
	s_addc_u32 s13, s13, 0
	global_load_dwordx4 v[238:241], v171, s[14:15]
	global_load_dwordx4 v[242:245], v171, s[12:13]
	s_waitcnt vmcnt(2)
	s_mov_b64 vcc, s[6:7]
	v_cndmask_b32_dpp v0, v200, v196, vcc row_ror:8 row_mask:0xf bank_mask:0xf
	v_cndmask_b32_dpp v1, v201, v197, vcc row_ror:8 row_mask:0xf bank_mask:0xf
	v_cndmask_b32_dpp v2, v202, v198, vcc row_ror:8 row_mask:0xf bank_mask:0xf
	v_cndmask_b32_dpp v3, v203, v199, vcc row_ror:8 row_mask:0xf bank_mask:0xf
	s_not_b64 vcc, s[6:7]
	v_cndmask_b32_dpp v4, v196, v200, vcc row_ror:8 row_mask:0xf bank_mask:0xf
	v_cndmask_b32_dpp v5, v197, v201, vcc row_ror:8 row_mask:0xf bank_mask:0xf
	v_cndmask_b32_dpp v6, v198, v202, vcc row_ror:8 row_mask:0xf bank_mask:0xf
	v_cndmask_b32_dpp v7, v199, v203, vcc row_ror:8 row_mask:0xf bank_mask:0xf
	s_add_u32 s14, s14, 0x8000
	s_addc_u32 s15, s15, 0
	s_add_u32 s12, s12, 0x8000
	s_addc_u32 s13, s13, 0
	global_load_dwordx4 v[196:199], v171, s[14:15]
	global_load_dwordx4 v[200:203], v171, s[12:13]
	v_lshlrev_b32_e32 v246, 16, v0
	v_and_b32_e32 v247, 0xffff0000, v0
	v_pk_fma_f32 v[134:135], v[134:135], v[142:143], v[246:247]
	v_lshlrev_b32_e32 v248, 16, v1
	v_and_b32_e32 v249, 0xffff0000, v1
	v_pk_fma_f32 v[136:137], v[136:137], v[144:145], v[248:249]
	v_lshlrev_b32_e32 v250, 16, v2
	v_and_b32_e32 v251, 0xffff0000, v2
	v_pk_fma_f32 v[130:131], v[130:131], v[150:151], v[250:251]
	v_lshlrev_b32_e32 v208, 16, v3
	v_and_b32_e32 v209, 0xffff0000, v3
	v_pk_fma_f32 v[132:133], v[132:133], v[152:153], v[208:209]
	v_lshlrev_b32_e32 v246, 16, v4
	v_and_b32_e32 v247, 0xffff0000, v4
	v_pk_fma_f32 v[126:127], v[126:127], v[138:139], v[246:247]
	v_lshlrev_b32_e32 v248, 16, v5
	v_and_b32_e32 v249, 0xffff0000, v5
	v_pk_fma_f32 v[128:129], v[128:129], v[140:141], v[248:249]
	v_lshlrev_b32_e32 v250, 16, v6
	v_and_b32_e32 v251, 0xffff0000, v6
	v_pk_fma_f32 v[122:123], v[122:123], v[146:147], v[250:251]
	v_lshlrev_b32_e32 v208, 16, v7
	v_and_b32_e32 v209, 0xffff0000, v7
	v_pk_fma_f32 v[124:125], v[124:125], v[148:149], v[208:209]
	v_cvt_pk_bf16_f32 v0, v134, v135
	v_cvt_pk_bf16_f32 v1, v136, v137
	v_cvt_pk_bf16_f32 v2, v130, v131
	v_cvt_pk_bf16_f32 v3, v132, v133
	v_cvt_pk_bf16_f32 v4, v126, v127
	v_cvt_pk_bf16_f32 v5, v128, v129
	v_cvt_pk_bf16_f32 v6, v122, v123
	v_cvt_pk_bf16_f32 v7, v124, v125
	v_mul_f32_e32 v246, v135, v135
	v_mul_f32_e32 v248, v137, v137
	v_fmac_f32_e32 v246, v134, v134
	v_fmac_f32_e32 v248, v136, v136
	v_add_f32_e32 v246, v246, v248
	v_mul_f32_e32 v248, v131, v131
	v_fmac_f32_e32 v248, v130, v130
	v_add_f32_e32 v246, v246, v248
	v_mul_f32_e32 v248, v133, v133
	v_fmac_f32_e32 v248, v132, v132
	v_add_f32_e32 v246, v248, v246
	v_mul_f32_e32 v247, v127, v127
	v_mul_f32_e32 v248, v129, v129
	v_fmac_f32_e32 v247, v126, v126
	v_fmac_f32_e32 v248, v128, v128
	v_add_f32_e32 v247, v247, v248
	v_mul_f32_e32 v248, v123, v123
	v_fmac_f32_e32 v248, v122, v122
	v_add_f32_e32 v247, v247, v248
	v_mul_f32_e32 v248, v125, v125
	v_fmac_f32_e32 v248, v124, v124
	v_add_f32_e32 v247, v248, v247
	v_add_f32_e32 v246, v246, v247
	v_mov_b32_e32 v247, v246
	s_nop 1
	v_permlane16_swap_b32_e32 v246, v247
	s_nop 1
	v_add_f32_e32 v246, v246, v247
	v_mov_b32_e32 v247, v246
	s_nop 1
	v_permlane32_swap_b32_e32 v246, v247
	v_add_u32_e32 v248, s8, v223
	s_nop 0
	v_add_f32_e32 v246, v246, v247
	s_mov_b64 exec, s[44:45]
	ds_write_b32 v248, v246
	s_mov_b64 exec, -1
	v_pk_mul_f32 v[134:135], v[180:181], v[134:135]
	v_pk_mul_f32 v[136:137], v[182:183], v[136:137]
	v_pk_mul_f32 v[130:131], v[184:185], v[130:131]
	v_pk_mul_f32 v[132:133], v[186:187], v[132:133]
	v_pk_mul_f32 v[126:127], v[188:189], v[126:127]
	v_pk_mul_f32 v[128:129], v[190:191], v[128:129]
	v_pk_mul_f32 v[122:123], v[192:193], v[122:123]
	v_pk_mul_f32 v[124:125], v[194:195], v[124:125]
	v_cvt_pk_bf16_f32 v246, v134, v135
	v_cvt_pk_bf16_f32 v247, v136, v137
	v_cvt_pk_bf16_f32 v248, v130, v131
	v_cvt_pk_bf16_f32 v249, v132, v133
	v_cvt_pk_bf16_f32 v250, v126, v127
	v_cvt_pk_bf16_f32 v251, v128, v129
	v_cvt_pk_bf16_f32 v208, v122, v123
	v_cvt_pk_bf16_f32 v209, v124, v125
	s_nop 1
	s_mov_b64 vcc, s[6:7]
	v_cndmask_b32_dpp v134, v4, v0, vcc row_ror:8 row_mask:0xf bank_mask:0xf
	v_cndmask_b32_dpp v135, v5, v1, vcc row_ror:8 row_mask:0xf bank_mask:0xf
	v_cndmask_b32_dpp v136, v6, v2, vcc row_ror:8 row_mask:0xf bank_mask:0xf
	v_cndmask_b32_dpp v137, v7, v3, vcc row_ror:8 row_mask:0xf bank_mask:0xf
	v_cndmask_b32_dpp v126, v250, v246, vcc row_ror:8 row_mask:0xf bank_mask:0xf
	v_cndmask_b32_dpp v127, v251, v247, vcc row_ror:8 row_mask:0xf bank_mask:0xf
	v_cndmask_b32_dpp v128, v208, v248, vcc row_ror:8 row_mask:0xf bank_mask:0xf
	v_cndmask_b32_dpp v129, v209, v249, vcc row_ror:8 row_mask:0xf bank_mask:0xf
	s_not_b64 vcc, s[6:7]
	v_cndmask_b32_dpp v130, v0, v4, vcc row_ror:8 row_mask:0xf bank_mask:0xf
	v_cndmask_b32_dpp v131, v1, v5, vcc row_ror:8 row_mask:0xf bank_mask:0xf
	v_cndmask_b32_dpp v132, v2, v6, vcc row_ror:8 row_mask:0xf bank_mask:0xf
	v_cndmask_b32_dpp v133, v3, v7, vcc row_ror:8 row_mask:0xf bank_mask:0xf
	v_cndmask_b32_dpp v122, v246, v250, vcc row_ror:8 row_mask:0xf bank_mask:0xf
	v_cndmask_b32_dpp v123, v247, v251, vcc row_ror:8 row_mask:0xf bank_mask:0xf
	v_cndmask_b32_dpp v124, v248, v208, vcc row_ror:8 row_mask:0xf bank_mask:0xf
	v_cndmask_b32_dpp v125, v249, v209, vcc row_ror:8 row_mask:0xf bank_mask:0xf
	global_store_dwordx4 v171, v[134:137], s[2:3]
	global_store_dwordx4 v171, v[130:133], s[18:19]
	global_store_dwordx4 v171, v[126:129], s[78:79]
	global_store_dwordx4 v171, v[122:125], s[22:23]
	s_waitcnt vmcnt(8)
	s_mov_b64 vcc, s[6:7]
	v_cndmask_b32_dpp v0, v234, v204, vcc row_ror:8 row_mask:0xf bank_mask:0xf
	v_cndmask_b32_dpp v1, v235, v205, vcc row_ror:8 row_mask:0xf bank_mask:0xf
	v_cndmask_b32_dpp v2, v236, v206, vcc row_ror:8 row_mask:0xf bank_mask:0xf
	v_cndmask_b32_dpp v3, v237, v207, vcc row_ror:8 row_mask:0xf bank_mask:0xf
	s_not_b64 vcc, s[6:7]
	v_cndmask_b32_dpp v4, v204, v234, vcc row_ror:8 row_mask:0xf bank_mask:0xf
	v_cndmask_b32_dpp v5, v205, v235, vcc row_ror:8 row_mask:0xf bank_mask:0xf
	v_cndmask_b32_dpp v6, v206, v236, vcc row_ror:8 row_mask:0xf bank_mask:0xf
	v_cndmask_b32_dpp v7, v207, v237, vcc row_ror:8 row_mask:0xf bank_mask:0xf
	s_add_u32 s14, s14, 0x28000
	s_addc_u32 s15, s15, 0
	s_add_u32 s12, s12, 0x28000
	s_addc_u32 s13, s13, 0
	global_load_dwordx4 v[204:207], v171, s[14:15]
	global_load_dwordx4 v[234:237], v171, s[12:13]
	v_lshlrev_b32_e32 v246, 16, v0
	v_and_b32_e32 v247, 0xffff0000, v0
	v_pk_fma_f32 v[118:119], v[118:119], v[142:143], v[246:247]
	v_lshlrev_b32_e32 v248, 16, v1
	v_and_b32_e32 v249, 0xffff0000, v1
	v_pk_fma_f32 v[120:121], v[120:121], v[144:145], v[248:249]
	v_lshlrev_b32_e32 v250, 16, v2
	v_and_b32_e32 v251, 0xffff0000, v2
	v_pk_fma_f32 v[114:115], v[114:115], v[150:151], v[250:251]
	v_lshlrev_b32_e32 v208, 16, v3
	v_and_b32_e32 v209, 0xffff0000, v3
	v_pk_fma_f32 v[116:117], v[116:117], v[152:153], v[208:209]
	v_lshlrev_b32_e32 v246, 16, v4
	v_and_b32_e32 v247, 0xffff0000, v4
	v_pk_fma_f32 v[110:111], v[110:111], v[138:139], v[246:247]
	v_lshlrev_b32_e32 v248, 16, v5
	v_and_b32_e32 v249, 0xffff0000, v5
	v_pk_fma_f32 v[112:113], v[112:113], v[140:141], v[248:249]
	v_lshlrev_b32_e32 v250, 16, v6
	v_and_b32_e32 v251, 0xffff0000, v6
	v_pk_fma_f32 v[106:107], v[106:107], v[146:147], v[250:251]
	v_lshlrev_b32_e32 v208, 16, v7
	v_and_b32_e32 v209, 0xffff0000, v7
	v_pk_fma_f32 v[108:109], v[108:109], v[148:149], v[208:209]
	v_cvt_pk_bf16_f32 v0, v118, v119
	v_cvt_pk_bf16_f32 v1, v120, v121
	v_cvt_pk_bf16_f32 v2, v114, v115
	v_cvt_pk_bf16_f32 v3, v116, v117
	v_cvt_pk_bf16_f32 v4, v110, v111
	v_cvt_pk_bf16_f32 v5, v112, v113
	v_cvt_pk_bf16_f32 v6, v106, v107
	v_cvt_pk_bf16_f32 v7, v108, v109
	v_mul_f32_e32 v246, v119, v119
	v_mul_f32_e32 v248, v121, v121
	v_fmac_f32_e32 v246, v118, v118
	v_fmac_f32_e32 v248, v120, v120
	v_add_f32_e32 v246, v246, v248
	v_mul_f32_e32 v248, v115, v115
	v_fmac_f32_e32 v248, v114, v114
	v_add_f32_e32 v246, v246, v248
	v_mul_f32_e32 v248, v117, v117
	v_fmac_f32_e32 v248, v116, v116
	v_add_f32_e32 v246, v248, v246
	v_mul_f32_e32 v247, v111, v111
	v_mul_f32_e32 v248, v113, v113
	v_fmac_f32_e32 v247, v110, v110
	v_fmac_f32_e32 v248, v112, v112
	v_add_f32_e32 v247, v247, v248
	v_mul_f32_e32 v248, v107, v107
	v_fmac_f32_e32 v248, v106, v106
	v_add_f32_e32 v247, v247, v248
	v_mul_f32_e32 v248, v109, v109
	v_fmac_f32_e32 v248, v108, v108
	v_add_f32_e32 v247, v248, v247
	v_add_f32_e32 v246, v246, v247
	v_mov_b32_e32 v247, v246
	s_nop 1
	v_permlane16_swap_b32_e32 v246, v247
	s_nop 1
	v_add_f32_e32 v246, v246, v247
	v_mov_b32_e32 v247, v246
	s_nop 1
	v_permlane32_swap_b32_e32 v246, v247
	v_add_u32_e32 v248, s8, v223
	s_nop 0
	v_add_f32_e32 v246, v246, v247
	s_mov_b64 exec, s[44:45]
	ds_write_b32 v248, v246 offset:256
	s_mov_b64 exec, -1
	v_pk_mul_f32 v[118:119], v[180:181], v[118:119]
	v_pk_mul_f32 v[120:121], v[182:183], v[120:121]
	v_pk_mul_f32 v[114:115], v[184:185], v[114:115]
	v_pk_mul_f32 v[116:117], v[186:187], v[116:117]
	v_pk_mul_f32 v[110:111], v[188:189], v[110:111]
	v_pk_mul_f32 v[112:113], v[190:191], v[112:113]
	v_pk_mul_f32 v[106:107], v[192:193], v[106:107]
	v_pk_mul_f32 v[108:109], v[194:195], v[108:109]
	v_cvt_pk_bf16_f32 v246, v118, v119
	v_cvt_pk_bf16_f32 v247, v120, v121
	v_cvt_pk_bf16_f32 v248, v114, v115
	v_cvt_pk_bf16_f32 v249, v116, v117
	v_cvt_pk_bf16_f32 v250, v110, v111
	v_cvt_pk_bf16_f32 v251, v112, v113
	v_cvt_pk_bf16_f32 v208, v106, v107
	v_cvt_pk_bf16_f32 v209, v108, v109
	s_add_u32 s2, s2, 0x8000
	s_addc_u32 s3, s3, 0
	s_add_u32 s18, s18, 0x8000
	s_addc_u32 s19, s19, 0
	s_add_u32 s78, s78, 0x8000
	s_addc_u32 s79, s79, 0
	s_add_u32 s22, s22, 0x8000
	s_addc_u32 s23, s23, 0
	s_mov_b64 vcc, s[6:7]
	v_cndmask_b32_dpp v118, v4, v0, vcc row_ror:8 row_mask:0xf bank_mask:0xf
	v_cndmask_b32_dpp v119, v5, v1, vcc row_ror:8 row_mask:0xf bank_mask:0xf
	v_cndmask_b32_dpp v120, v6, v2, vcc row_ror:8 row_mask:0xf bank_mask:0xf
	v_cndmask_b32_dpp v121, v7, v3, vcc row_ror:8 row_mask:0xf bank_mask:0xf
	v_cndmask_b32_dpp v110, v250, v246, vcc row_ror:8 row_mask:0xf bank_mask:0xf
	v_cndmask_b32_dpp v111, v251, v247, vcc row_ror:8 row_mask:0xf bank_mask:0xf
	v_cndmask_b32_dpp v112, v208, v248, vcc row_ror:8 row_mask:0xf bank_mask:0xf
	v_cndmask_b32_dpp v113, v209, v249, vcc row_ror:8 row_mask:0xf bank_mask:0xf
	s_not_b64 vcc, s[6:7]
	v_cndmask_b32_dpp v114, v0, v4, vcc row_ror:8 row_mask:0xf bank_mask:0xf
	v_cndmask_b32_dpp v115, v1, v5, vcc row_ror:8 row_mask:0xf bank_mask:0xf
	v_cndmask_b32_dpp v116, v2, v6, vcc row_ror:8 row_mask:0xf bank_mask:0xf
	v_cndmask_b32_dpp v117, v3, v7, vcc row_ror:8 row_mask:0xf bank_mask:0xf
	v_cndmask_b32_dpp v106, v246, v250, vcc row_ror:8 row_mask:0xf bank_mask:0xf
	v_cndmask_b32_dpp v107, v247, v251, vcc row_ror:8 row_mask:0xf bank_mask:0xf
	v_cndmask_b32_dpp v108, v248, v208, vcc row_ror:8 row_mask:0xf bank_mask:0xf
	v_cndmask_b32_dpp v109, v249, v209, vcc row_ror:8 row_mask:0xf bank_mask:0xf
	global_store_dwordx4 v171, v[118:121], s[2:3]
	global_store_dwordx4 v171, v[114:117], s[18:19]
	global_store_dwordx4 v171, v[110:113], s[78:79]
	global_store_dwordx4 v171, v[106:109], s[22:23]
	s_waitcnt vmcnt(12)
	s_mov_b64 vcc, s[6:7]
	v_cndmask_b32_dpp v0, v242, v238, vcc row_ror:8 row_mask:0xf bank_mask:0xf
	v_cndmask_b32_dpp v1, v243, v239, vcc row_ror:8 row_mask:0xf bank_mask:0xf
	v_cndmask_b32_dpp v2, v244, v240, vcc row_ror:8 row_mask:0xf bank_mask:0xf
	v_cndmask_b32_dpp v3, v245, v241, vcc row_ror:8 row_mask:0xf bank_mask:0xf
	s_not_b64 vcc, s[6:7]
	v_cndmask_b32_dpp v4, v238, v242, vcc row_ror:8 row_mask:0xf bank_mask:0xf
	v_cndmask_b32_dpp v5, v239, v243, vcc row_ror:8 row_mask:0xf bank_mask:0xf
	v_cndmask_b32_dpp v6, v240, v244, vcc row_ror:8 row_mask:0xf bank_mask:0xf
	v_cndmask_b32_dpp v7, v241, v245, vcc row_ror:8 row_mask:0xf bank_mask:0xf
	s_add_u32 s14, s14, 0x8000
	s_addc_u32 s15, s15, 0
	s_add_u32 s12, s12, 0x8000
	s_addc_u32 s13, s13, 0
	global_load_dwordx4 v[238:241], v171, s[14:15]
	global_load_dwordx4 v[242:245], v171, s[12:13]
	v_lshlrev_b32_e32 v246, 16, v0
	v_and_b32_e32 v247, 0xffff0000, v0
	v_pk_fma_f32 v[102:103], v[102:103], v[142:143], v[246:247]
	v_lshlrev_b32_e32 v248, 16, v1
	v_and_b32_e32 v249, 0xffff0000, v1
	v_pk_fma_f32 v[104:105], v[104:105], v[144:145], v[248:249]
	v_lshlrev_b32_e32 v250, 16, v2
	v_and_b32_e32 v251, 0xffff0000, v2
	v_pk_fma_f32 v[98:99], v[98:99], v[150:151], v[250:251]
	v_lshlrev_b32_e32 v208, 16, v3
	v_and_b32_e32 v209, 0xffff0000, v3
	v_pk_fma_f32 v[100:101], v[100:101], v[152:153], v[208:209]
	v_lshlrev_b32_e32 v246, 16, v4
	v_and_b32_e32 v247, 0xffff0000, v4
	v_pk_fma_f32 v[92:93], v[92:93], v[138:139], v[246:247]
	v_lshlrev_b32_e32 v248, 16, v5
	v_and_b32_e32 v249, 0xffff0000, v5
	v_pk_fma_f32 v[94:95], v[94:95], v[140:141], v[248:249]
	v_lshlrev_b32_e32 v250, 16, v6
	v_and_b32_e32 v251, 0xffff0000, v6
	v_pk_fma_f32 v[88:89], v[88:89], v[146:147], v[250:251]
	v_lshlrev_b32_e32 v208, 16, v7
	v_and_b32_e32 v209, 0xffff0000, v7
	v_pk_fma_f32 v[90:91], v[90:91], v[148:149], v[208:209]
	v_cvt_pk_bf16_f32 v0, v102, v103
	v_cvt_pk_bf16_f32 v1, v104, v105
	v_cvt_pk_bf16_f32 v2, v98, v99
	v_cvt_pk_bf16_f32 v3, v100, v101
	v_cvt_pk_bf16_f32 v4, v92, v93
	v_cvt_pk_bf16_f32 v5, v94, v95
	v_cvt_pk_bf16_f32 v6, v88, v89
	v_cvt_pk_bf16_f32 v7, v90, v91
	v_mul_f32_e32 v246, v103, v103
	v_mul_f32_e32 v248, v105, v105
	v_fmac_f32_e32 v246, v102, v102
	v_fmac_f32_e32 v248, v104, v104
	v_add_f32_e32 v246, v246, v248
	v_mul_f32_e32 v248, v99, v99
	v_fmac_f32_e32 v248, v98, v98
	v_add_f32_e32 v246, v246, v248
	v_mul_f32_e32 v248, v101, v101
	v_fmac_f32_e32 v248, v100, v100
	v_add_f32_e32 v246, v248, v246
	v_mul_f32_e32 v247, v93, v93
	v_mul_f32_e32 v248, v95, v95
	v_fmac_f32_e32 v247, v92, v92
	v_fmac_f32_e32 v248, v94, v94
	v_add_f32_e32 v247, v247, v248
	v_mul_f32_e32 v248, v89, v89
	v_fmac_f32_e32 v248, v88, v88
	v_add_f32_e32 v247, v247, v248
	v_mul_f32_e32 v248, v91, v91
	v_fmac_f32_e32 v248, v90, v90
	v_add_f32_e32 v247, v248, v247
	v_add_f32_e32 v246, v246, v247
	v_mov_b32_e32 v247, v246
	s_nop 1
	v_permlane16_swap_b32_e32 v246, v247
	s_nop 1
	v_add_f32_e32 v246, v246, v247
	v_mov_b32_e32 v247, v246
	s_nop 1
	v_permlane32_swap_b32_e32 v246, v247
	v_add_u32_e32 v248, s8, v223
	s_nop 0
	v_add_f32_e32 v246, v246, v247
	s_mov_b64 exec, s[44:45]
	ds_write_b32 v248, v246 offset:512
	s_mov_b64 exec, -1
	v_pk_mul_f32 v[102:103], v[180:181], v[102:103]
	v_pk_mul_f32 v[104:105], v[182:183], v[104:105]
	v_pk_mul_f32 v[98:99], v[184:185], v[98:99]
	v_pk_mul_f32 v[100:101], v[186:187], v[100:101]
	v_pk_mul_f32 v[92:93], v[188:189], v[92:93]
	v_pk_mul_f32 v[94:95], v[190:191], v[94:95]
	v_pk_mul_f32 v[88:89], v[192:193], v[88:89]
	v_pk_mul_f32 v[90:91], v[194:195], v[90:91]
	v_cvt_pk_bf16_f32 v246, v102, v103
	v_cvt_pk_bf16_f32 v247, v104, v105
	v_cvt_pk_bf16_f32 v248, v98, v99
	v_cvt_pk_bf16_f32 v249, v100, v101
	v_cvt_pk_bf16_f32 v250, v92, v93
	v_cvt_pk_bf16_f32 v251, v94, v95
	v_cvt_pk_bf16_f32 v208, v88, v89
	v_cvt_pk_bf16_f32 v209, v90, v91
	s_add_u32 s2, s2, 0x8000
	s_addc_u32 s3, s3, 0
	s_add_u32 s18, s18, 0x8000
	s_addc_u32 s19, s19, 0
	s_add_u32 s78, s78, 0x8000
	s_addc_u32 s79, s79, 0
	s_add_u32 s22, s22, 0x8000
	s_addc_u32 s23, s23, 0
	s_mov_b64 vcc, s[6:7]
	v_cndmask_b32_dpp v102, v4, v0, vcc row_ror:8 row_mask:0xf bank_mask:0xf
	v_cndmask_b32_dpp v103, v5, v1, vcc row_ror:8 row_mask:0xf bank_mask:0xf
	v_cndmask_b32_dpp v104, v6, v2, vcc row_ror:8 row_mask:0xf bank_mask:0xf
	v_cndmask_b32_dpp v105, v7, v3, vcc row_ror:8 row_mask:0xf bank_mask:0xf
	v_cndmask_b32_dpp v92, v250, v246, vcc row_ror:8 row_mask:0xf bank_mask:0xf
	v_cndmask_b32_dpp v93, v251, v247, vcc row_ror:8 row_mask:0xf bank_mask:0xf
	v_cndmask_b32_dpp v94, v208, v248, vcc row_ror:8 row_mask:0xf bank_mask:0xf
	v_cndmask_b32_dpp v95, v209, v249, vcc row_ror:8 row_mask:0xf bank_mask:0xf
	s_not_b64 vcc, s[6:7]
	v_cndmask_b32_dpp v98, v0, v4, vcc row_ror:8 row_mask:0xf bank_mask:0xf
	v_cndmask_b32_dpp v99, v1, v5, vcc row_ror:8 row_mask:0xf bank_mask:0xf
	v_cndmask_b32_dpp v100, v2, v6, vcc row_ror:8 row_mask:0xf bank_mask:0xf
	v_cndmask_b32_dpp v101, v3, v7, vcc row_ror:8 row_mask:0xf bank_mask:0xf
	v_cndmask_b32_dpp v88, v246, v250, vcc row_ror:8 row_mask:0xf bank_mask:0xf
	v_cndmask_b32_dpp v89, v247, v251, vcc row_ror:8 row_mask:0xf bank_mask:0xf
	v_cndmask_b32_dpp v90, v248, v208, vcc row_ror:8 row_mask:0xf bank_mask:0xf
	v_cndmask_b32_dpp v91, v249, v209, vcc row_ror:8 row_mask:0xf bank_mask:0xf
	global_store_dwordx4 v171, v[102:105], s[2:3]
	global_store_dwordx4 v171, v[98:101], s[18:19]
	global_store_dwordx4 v171, v[92:95], s[78:79]
	global_store_dwordx4 v171, v[88:91], s[22:23]
	s_waitcnt vmcnt(16)
	s_mov_b64 vcc, s[6:7]
	v_cndmask_b32_dpp v0, v200, v196, vcc row_ror:8 row_mask:0xf bank_mask:0xf
	v_cndmask_b32_dpp v1, v201, v197, vcc row_ror:8 row_mask:0xf bank_mask:0xf
	v_cndmask_b32_dpp v2, v202, v198, vcc row_ror:8 row_mask:0xf bank_mask:0xf
	v_cndmask_b32_dpp v3, v203, v199, vcc row_ror:8 row_mask:0xf bank_mask:0xf
	s_not_b64 vcc, s[6:7]
	v_cndmask_b32_dpp v4, v196, v200, vcc row_ror:8 row_mask:0xf bank_mask:0xf
	v_cndmask_b32_dpp v5, v197, v201, vcc row_ror:8 row_mask:0xf bank_mask:0xf
	v_cndmask_b32_dpp v6, v198, v202, vcc row_ror:8 row_mask:0xf bank_mask:0xf
	v_cndmask_b32_dpp v7, v199, v203, vcc row_ror:8 row_mask:0xf bank_mask:0xf
	s_add_u32 s14, s14, 0x8000
	s_addc_u32 s15, s15, 0
	s_add_u32 s12, s12, 0x8000
	s_addc_u32 s13, s13, 0
	global_load_dwordx4 v[196:199], v171, s[14:15]
	global_load_dwordx4 v[200:203], v171, s[12:13]
	v_lshlrev_b32_e32 v246, 16, v0
	v_and_b32_e32 v247, 0xffff0000, v0
	v_pk_fma_f32 v[84:85], v[84:85], v[142:143], v[246:247]
	v_lshlrev_b32_e32 v248, 16, v1
	v_and_b32_e32 v249, 0xffff0000, v1
	v_pk_fma_f32 v[86:87], v[86:87], v[144:145], v[248:249]
	v_lshlrev_b32_e32 v250, 16, v2
	v_and_b32_e32 v251, 0xffff0000, v2
	v_pk_fma_f32 v[80:81], v[80:81], v[150:151], v[250:251]
	v_lshlrev_b32_e32 v208, 16, v3
	v_and_b32_e32 v209, 0xffff0000, v3
	v_pk_fma_f32 v[82:83], v[82:83], v[152:153], v[208:209]
	v_lshlrev_b32_e32 v246, 16, v4
	v_and_b32_e32 v247, 0xffff0000, v4
	v_pk_fma_f32 v[76:77], v[76:77], v[138:139], v[246:247]
	v_lshlrev_b32_e32 v248, 16, v5
	v_and_b32_e32 v249, 0xffff0000, v5
	v_pk_fma_f32 v[78:79], v[78:79], v[140:141], v[248:249]
	v_lshlrev_b32_e32 v250, 16, v6
	v_and_b32_e32 v251, 0xffff0000, v6
	v_pk_fma_f32 v[72:73], v[72:73], v[146:147], v[250:251]
	v_lshlrev_b32_e32 v208, 16, v7
	v_and_b32_e32 v209, 0xffff0000, v7
	v_pk_fma_f32 v[74:75], v[74:75], v[148:149], v[208:209]
	v_cvt_pk_bf16_f32 v0, v84, v85
	v_cvt_pk_bf16_f32 v1, v86, v87
	v_cvt_pk_bf16_f32 v2, v80, v81
	v_cvt_pk_bf16_f32 v3, v82, v83
	v_cvt_pk_bf16_f32 v4, v76, v77
	v_cvt_pk_bf16_f32 v5, v78, v79
	v_cvt_pk_bf16_f32 v6, v72, v73
	v_cvt_pk_bf16_f32 v7, v74, v75
	v_mul_f32_e32 v246, v85, v85
	v_mul_f32_e32 v248, v87, v87
	v_fmac_f32_e32 v246, v84, v84
	v_fmac_f32_e32 v248, v86, v86
	v_add_f32_e32 v246, v246, v248
	v_mul_f32_e32 v248, v81, v81
	v_fmac_f32_e32 v248, v80, v80
	v_add_f32_e32 v246, v246, v248
	v_mul_f32_e32 v248, v83, v83
	v_fmac_f32_e32 v248, v82, v82
	v_add_f32_e32 v246, v248, v246
	v_mul_f32_e32 v247, v77, v77
	v_mul_f32_e32 v248, v79, v79
	v_fmac_f32_e32 v247, v76, v76
	v_fmac_f32_e32 v248, v78, v78
	v_add_f32_e32 v247, v247, v248
	v_mul_f32_e32 v248, v73, v73
	v_fmac_f32_e32 v248, v72, v72
	v_add_f32_e32 v247, v247, v248
	v_mul_f32_e32 v248, v75, v75
	v_fmac_f32_e32 v248, v74, v74
	v_add_f32_e32 v247, v248, v247
	v_add_f32_e32 v246, v246, v247
	v_mov_b32_e32 v247, v246
	s_nop 1
	v_permlane16_swap_b32_e32 v246, v247
	s_nop 1
	v_add_f32_e32 v246, v246, v247
	v_mov_b32_e32 v247, v246
	s_nop 1
	v_permlane32_swap_b32_e32 v246, v247
	v_add_u32_e32 v248, s8, v223
	s_nop 0
	v_add_f32_e32 v246, v246, v247
	s_mov_b64 exec, s[44:45]
	ds_write_b32 v248, v246 offset:768
	s_mov_b64 exec, -1
	v_pk_mul_f32 v[84:85], v[180:181], v[84:85]
	v_pk_mul_f32 v[86:87], v[182:183], v[86:87]
	v_pk_mul_f32 v[80:81], v[184:185], v[80:81]
	v_pk_mul_f32 v[82:83], v[186:187], v[82:83]
	v_pk_mul_f32 v[76:77], v[188:189], v[76:77]
	v_pk_mul_f32 v[78:79], v[190:191], v[78:79]
	v_pk_mul_f32 v[72:73], v[192:193], v[72:73]
	v_pk_mul_f32 v[74:75], v[194:195], v[74:75]
	v_cvt_pk_bf16_f32 v246, v84, v85
	v_cvt_pk_bf16_f32 v247, v86, v87
	v_cvt_pk_bf16_f32 v248, v80, v81
	v_cvt_pk_bf16_f32 v249, v82, v83
	v_cvt_pk_bf16_f32 v250, v76, v77
	v_cvt_pk_bf16_f32 v251, v78, v79
	v_cvt_pk_bf16_f32 v208, v72, v73
	v_cvt_pk_bf16_f32 v209, v74, v75
	s_add_u32 s2, s2, 0x8000
	s_addc_u32 s3, s3, 0
	s_add_u32 s18, s18, 0x8000
	s_addc_u32 s19, s19, 0
	s_add_u32 s78, s78, 0x8000
	s_addc_u32 s79, s79, 0
	s_add_u32 s22, s22, 0x8000
	s_addc_u32 s23, s23, 0
	s_mov_b64 vcc, s[6:7]
	v_cndmask_b32_dpp v84, v4, v0, vcc row_ror:8 row_mask:0xf bank_mask:0xf
	v_cndmask_b32_dpp v85, v5, v1, vcc row_ror:8 row_mask:0xf bank_mask:0xf
	v_cndmask_b32_dpp v86, v6, v2, vcc row_ror:8 row_mask:0xf bank_mask:0xf
	v_cndmask_b32_dpp v87, v7, v3, vcc row_ror:8 row_mask:0xf bank_mask:0xf
	v_cndmask_b32_dpp v76, v250, v246, vcc row_ror:8 row_mask:0xf bank_mask:0xf
	v_cndmask_b32_dpp v77, v251, v247, vcc row_ror:8 row_mask:0xf bank_mask:0xf
	v_cndmask_b32_dpp v78, v208, v248, vcc row_ror:8 row_mask:0xf bank_mask:0xf
	v_cndmask_b32_dpp v79, v209, v249, vcc row_ror:8 row_mask:0xf bank_mask:0xf
	s_not_b64 vcc, s[6:7]
	v_cndmask_b32_dpp v80, v0, v4, vcc row_ror:8 row_mask:0xf bank_mask:0xf
	v_cndmask_b32_dpp v81, v1, v5, vcc row_ror:8 row_mask:0xf bank_mask:0xf
	v_cndmask_b32_dpp v82, v2, v6, vcc row_ror:8 row_mask:0xf bank_mask:0xf
	v_cndmask_b32_dpp v83, v3, v7, vcc row_ror:8 row_mask:0xf bank_mask:0xf
	v_cndmask_b32_dpp v72, v246, v250, vcc row_ror:8 row_mask:0xf bank_mask:0xf
	v_cndmask_b32_dpp v73, v247, v251, vcc row_ror:8 row_mask:0xf bank_mask:0xf
	v_cndmask_b32_dpp v74, v248, v208, vcc row_ror:8 row_mask:0xf bank_mask:0xf
	v_cndmask_b32_dpp v75, v249, v209, vcc row_ror:8 row_mask:0xf bank_mask:0xf
	global_store_dwordx4 v171, v[84:87], s[2:3]
	global_store_dwordx4 v171, v[80:83], s[18:19]
	global_store_dwordx4 v171, v[76:79], s[78:79]
	global_store_dwordx4 v171, v[72:75], s[22:23]
	s_waitcnt vmcnt(16)
	s_mov_b64 vcc, s[6:7]
	v_cndmask_b32_dpp v0, v234, v204, vcc row_ror:8 row_mask:0xf bank_mask:0xf
	v_cndmask_b32_dpp v1, v235, v205, vcc row_ror:8 row_mask:0xf bank_mask:0xf
	v_cndmask_b32_dpp v2, v236, v206, vcc row_ror:8 row_mask:0xf bank_mask:0xf
	v_cndmask_b32_dpp v3, v237, v207, vcc row_ror:8 row_mask:0xf bank_mask:0xf
	s_not_b64 vcc, s[6:7]
	v_cndmask_b32_dpp v4, v204, v234, vcc row_ror:8 row_mask:0xf bank_mask:0xf
	v_cndmask_b32_dpp v5, v205, v235, vcc row_ror:8 row_mask:0xf bank_mask:0xf
	v_cndmask_b32_dpp v6, v206, v236, vcc row_ror:8 row_mask:0xf bank_mask:0xf
	v_cndmask_b32_dpp v7, v207, v237, vcc row_ror:8 row_mask:0xf bank_mask:0xf
	s_add_u32 s14, s14, 0x8000
	s_addc_u32 s15, s15, 0
	s_add_u32 s12, s12, 0x8000
	s_addc_u32 s13, s13, 0
	global_load_dwordx4 v[204:207], v171, s[14:15]
	global_load_dwordx4 v[234:237], v171, s[12:13]
	v_lshlrev_b32_e32 v246, 16, v0
	v_and_b32_e32 v247, 0xffff0000, v0
	v_pk_fma_f32 v[68:69], v[68:69], v[142:143], v[246:247]
	v_lshlrev_b32_e32 v248, 16, v1
	v_and_b32_e32 v249, 0xffff0000, v1
	v_pk_fma_f32 v[70:71], v[70:71], v[144:145], v[248:249]
	v_lshlrev_b32_e32 v250, 16, v2
	v_and_b32_e32 v251, 0xffff0000, v2
	v_pk_fma_f32 v[64:65], v[64:65], v[150:151], v[250:251]
	v_lshlrev_b32_e32 v208, 16, v3
	v_and_b32_e32 v209, 0xffff0000, v3
	v_pk_fma_f32 v[66:67], v[66:67], v[152:153], v[208:209]
	v_lshlrev_b32_e32 v246, 16, v4
	v_and_b32_e32 v247, 0xffff0000, v4
	v_pk_fma_f32 v[60:61], v[60:61], v[138:139], v[246:247]
	v_lshlrev_b32_e32 v248, 16, v5
	v_and_b32_e32 v249, 0xffff0000, v5
	v_pk_fma_f32 v[62:63], v[62:63], v[140:141], v[248:249]
	v_lshlrev_b32_e32 v250, 16, v6
	v_and_b32_e32 v251, 0xffff0000, v6
	v_pk_fma_f32 v[56:57], v[56:57], v[146:147], v[250:251]
	v_lshlrev_b32_e32 v208, 16, v7
	v_and_b32_e32 v209, 0xffff0000, v7
	v_pk_fma_f32 v[58:59], v[58:59], v[148:149], v[208:209]
	v_cvt_pk_bf16_f32 v0, v68, v69
	v_cvt_pk_bf16_f32 v1, v70, v71
	v_cvt_pk_bf16_f32 v2, v64, v65
	v_cvt_pk_bf16_f32 v3, v66, v67
	v_cvt_pk_bf16_f32 v4, v60, v61
	v_cvt_pk_bf16_f32 v5, v62, v63
	v_cvt_pk_bf16_f32 v6, v56, v57
	v_cvt_pk_bf16_f32 v7, v58, v59
	v_mul_f32_e32 v246, v69, v69
	v_mul_f32_e32 v248, v71, v71
	v_fmac_f32_e32 v246, v68, v68
	v_fmac_f32_e32 v248, v70, v70
	v_add_f32_e32 v246, v246, v248
	v_mul_f32_e32 v248, v65, v65
	v_fmac_f32_e32 v248, v64, v64
	v_add_f32_e32 v246, v246, v248
	v_mul_f32_e32 v248, v67, v67
	v_fmac_f32_e32 v248, v66, v66
	v_add_f32_e32 v246, v248, v246
	v_mul_f32_e32 v247, v61, v61
	v_mul_f32_e32 v248, v63, v63
	v_fmac_f32_e32 v247, v60, v60
	v_fmac_f32_e32 v248, v62, v62
	v_add_f32_e32 v247, v247, v248
	v_mul_f32_e32 v248, v57, v57
	v_fmac_f32_e32 v248, v56, v56
	v_add_f32_e32 v247, v247, v248
	v_mul_f32_e32 v248, v59, v59
	v_fmac_f32_e32 v248, v58, v58
	v_add_f32_e32 v247, v248, v247
	v_add_f32_e32 v246, v246, v247
	v_mov_b32_e32 v247, v246
	s_nop 1
	v_permlane16_swap_b32_e32 v246, v247
	s_nop 1
	v_add_f32_e32 v246, v246, v247
	v_mov_b32_e32 v247, v246
	s_nop 1
	v_permlane32_swap_b32_e32 v246, v247
	v_add_u32_e32 v248, s8, v223
	s_nop 0
	v_add_f32_e32 v246, v246, v247
	s_mov_b64 exec, s[44:45]
	ds_write_b32 v248, v246 offset:2048
	s_mov_b64 exec, -1
	v_pk_mul_f32 v[68:69], v[180:181], v[68:69]
	v_pk_mul_f32 v[70:71], v[182:183], v[70:71]
	v_pk_mul_f32 v[64:65], v[184:185], v[64:65]
	v_pk_mul_f32 v[66:67], v[186:187], v[66:67]
	v_pk_mul_f32 v[60:61], v[188:189], v[60:61]
	v_pk_mul_f32 v[62:63], v[190:191], v[62:63]
	v_pk_mul_f32 v[56:57], v[192:193], v[56:57]
	v_pk_mul_f32 v[58:59], v[194:195], v[58:59]
	v_cvt_pk_bf16_f32 v246, v68, v69
	v_cvt_pk_bf16_f32 v247, v70, v71
	v_cvt_pk_bf16_f32 v248, v64, v65
	v_cvt_pk_bf16_f32 v249, v66, v67
	v_cvt_pk_bf16_f32 v250, v60, v61
	v_cvt_pk_bf16_f32 v251, v62, v63
	v_cvt_pk_bf16_f32 v208, v56, v57
	v_cvt_pk_bf16_f32 v209, v58, v59
	s_add_u32 s2, s2, 0x28000
	s_addc_u32 s3, s3, 0
	s_add_u32 s18, s18, 0x28000
	s_addc_u32 s19, s19, 0
	s_add_u32 s78, s78, 0x28000
	s_addc_u32 s79, s79, 0
	s_add_u32 s22, s22, 0x28000
	s_addc_u32 s23, s23, 0
	s_mov_b64 vcc, s[6:7]
	v_cndmask_b32_dpp v68, v4, v0, vcc row_ror:8 row_mask:0xf bank_mask:0xf
	v_cndmask_b32_dpp v69, v5, v1, vcc row_ror:8 row_mask:0xf bank_mask:0xf
	v_cndmask_b32_dpp v70, v6, v2, vcc row_ror:8 row_mask:0xf bank_mask:0xf
	v_cndmask_b32_dpp v71, v7, v3, vcc row_ror:8 row_mask:0xf bank_mask:0xf
	v_cndmask_b32_dpp v60, v250, v246, vcc row_ror:8 row_mask:0xf bank_mask:0xf
	v_cndmask_b32_dpp v61, v251, v247, vcc row_ror:8 row_mask:0xf bank_mask:0xf
	v_cndmask_b32_dpp v62, v208, v248, vcc row_ror:8 row_mask:0xf bank_mask:0xf
	v_cndmask_b32_dpp v63, v209, v249, vcc row_ror:8 row_mask:0xf bank_mask:0xf
	s_not_b64 vcc, s[6:7]
	v_cndmask_b32_dpp v64, v0, v4, vcc row_ror:8 row_mask:0xf bank_mask:0xf
	v_cndmask_b32_dpp v65, v1, v5, vcc row_ror:8 row_mask:0xf bank_mask:0xf
	v_cndmask_b32_dpp v66, v2, v6, vcc row_ror:8 row_mask:0xf bank_mask:0xf
	v_cndmask_b32_dpp v67, v3, v7, vcc row_ror:8 row_mask:0xf bank_mask:0xf
	v_cndmask_b32_dpp v56, v246, v250, vcc row_ror:8 row_mask:0xf bank_mask:0xf
	v_cndmask_b32_dpp v57, v247, v251, vcc row_ror:8 row_mask:0xf bank_mask:0xf
	v_cndmask_b32_dpp v58, v248, v208, vcc row_ror:8 row_mask:0xf bank_mask:0xf
	v_cndmask_b32_dpp v59, v249, v209, vcc row_ror:8 row_mask:0xf bank_mask:0xf
	global_store_dwordx4 v171, v[68:71], s[2:3]
	global_store_dwordx4 v171, v[64:67], s[18:19]
	global_store_dwordx4 v171, v[60:63], s[78:79]
	global_store_dwordx4 v171, v[56:59], s[22:23]
	s_waitcnt vmcnt(16)
	s_mov_b64 vcc, s[6:7]
	v_cndmask_b32_dpp v0, v242, v238, vcc row_ror:8 row_mask:0xf bank_mask:0xf
	v_cndmask_b32_dpp v1, v243, v239, vcc row_ror:8 row_mask:0xf bank_mask:0xf
	v_cndmask_b32_dpp v2, v244, v240, vcc row_ror:8 row_mask:0xf bank_mask:0xf
	v_cndmask_b32_dpp v3, v245, v241, vcc row_ror:8 row_mask:0xf bank_mask:0xf
	s_not_b64 vcc, s[6:7]
	v_cndmask_b32_dpp v4, v238, v242, vcc row_ror:8 row_mask:0xf bank_mask:0xf
	v_cndmask_b32_dpp v5, v239, v243, vcc row_ror:8 row_mask:0xf bank_mask:0xf
	v_cndmask_b32_dpp v6, v240, v244, vcc row_ror:8 row_mask:0xf bank_mask:0xf
	v_cndmask_b32_dpp v7, v241, v245, vcc row_ror:8 row_mask:0xf bank_mask:0xf
	v_lshlrev_b32_e32 v246, 16, v0
	v_and_b32_e32 v247, 0xffff0000, v0
	v_pk_fma_f32 v[52:53], v[52:53], v[142:143], v[246:247]
	v_lshlrev_b32_e32 v248, 16, v1
	v_and_b32_e32 v249, 0xffff0000, v1
	v_pk_fma_f32 v[54:55], v[54:55], v[144:145], v[248:249]
	v_lshlrev_b32_e32 v250, 16, v2
	v_and_b32_e32 v251, 0xffff0000, v2
	v_pk_fma_f32 v[48:49], v[48:49], v[150:151], v[250:251]
	v_lshlrev_b32_e32 v208, 16, v3
	v_and_b32_e32 v209, 0xffff0000, v3
	v_pk_fma_f32 v[50:51], v[50:51], v[152:153], v[208:209]
	v_lshlrev_b32_e32 v246, 16, v4
	v_and_b32_e32 v247, 0xffff0000, v4
	v_pk_fma_f32 v[44:45], v[44:45], v[138:139], v[246:247]
	v_lshlrev_b32_e32 v248, 16, v5
	v_and_b32_e32 v249, 0xffff0000, v5
	v_pk_fma_f32 v[46:47], v[46:47], v[140:141], v[248:249]
	v_lshlrev_b32_e32 v250, 16, v6
	v_and_b32_e32 v251, 0xffff0000, v6
	v_pk_fma_f32 v[40:41], v[40:41], v[146:147], v[250:251]
	v_lshlrev_b32_e32 v208, 16, v7
	v_and_b32_e32 v209, 0xffff0000, v7
	v_pk_fma_f32 v[42:43], v[42:43], v[148:149], v[208:209]
	v_cvt_pk_bf16_f32 v0, v52, v53
	v_cvt_pk_bf16_f32 v1, v54, v55
	v_cvt_pk_bf16_f32 v2, v48, v49
	v_cvt_pk_bf16_f32 v3, v50, v51
	v_cvt_pk_bf16_f32 v4, v44, v45
	v_cvt_pk_bf16_f32 v5, v46, v47
	v_cvt_pk_bf16_f32 v6, v40, v41
	v_cvt_pk_bf16_f32 v7, v42, v43
	v_mul_f32_e32 v246, v53, v53
	v_mul_f32_e32 v248, v55, v55
	v_fmac_f32_e32 v246, v52, v52
	v_fmac_f32_e32 v248, v54, v54
	v_add_f32_e32 v246, v246, v248
	v_mul_f32_e32 v248, v49, v49
	v_fmac_f32_e32 v248, v48, v48
	v_add_f32_e32 v246, v246, v248
	v_mul_f32_e32 v248, v51, v51
	v_fmac_f32_e32 v248, v50, v50
	v_add_f32_e32 v246, v248, v246
	v_mul_f32_e32 v247, v45, v45
	v_mul_f32_e32 v248, v47, v47
	v_fmac_f32_e32 v247, v44, v44
	v_fmac_f32_e32 v248, v46, v46
	v_add_f32_e32 v247, v247, v248
	v_mul_f32_e32 v248, v41, v41
	v_fmac_f32_e32 v248, v40, v40
	v_add_f32_e32 v247, v247, v248
	v_mul_f32_e32 v248, v43, v43
	v_fmac_f32_e32 v248, v42, v42
	v_add_f32_e32 v247, v248, v247
	v_add_f32_e32 v246, v246, v247
	v_mov_b32_e32 v247, v246
	s_nop 1
	v_permlane16_swap_b32_e32 v246, v247
	s_nop 1
	v_add_f32_e32 v246, v246, v247
	v_mov_b32_e32 v247, v246
	s_nop 1
	v_permlane32_swap_b32_e32 v246, v247
	v_add_u32_e32 v248, s8, v223
	s_nop 0
	v_add_f32_e32 v246, v246, v247
	s_mov_b64 exec, s[44:45]
	ds_write_b32 v248, v246 offset:2304
	s_mov_b64 exec, -1
	v_pk_mul_f32 v[52:53], v[180:181], v[52:53]
	v_pk_mul_f32 v[54:55], v[182:183], v[54:55]
	v_pk_mul_f32 v[48:49], v[184:185], v[48:49]
	v_pk_mul_f32 v[50:51], v[186:187], v[50:51]
	v_pk_mul_f32 v[44:45], v[188:189], v[44:45]
	v_pk_mul_f32 v[46:47], v[190:191], v[46:47]
	v_pk_mul_f32 v[40:41], v[192:193], v[40:41]
	v_pk_mul_f32 v[42:43], v[194:195], v[42:43]
	v_cvt_pk_bf16_f32 v246, v52, v53
	v_cvt_pk_bf16_f32 v247, v54, v55
	v_cvt_pk_bf16_f32 v248, v48, v49
	v_cvt_pk_bf16_f32 v249, v50, v51
	v_cvt_pk_bf16_f32 v250, v44, v45
	v_cvt_pk_bf16_f32 v251, v46, v47
	v_cvt_pk_bf16_f32 v208, v40, v41
	v_cvt_pk_bf16_f32 v209, v42, v43
	s_add_u32 s2, s2, 0x8000
	s_addc_u32 s3, s3, 0
	s_add_u32 s18, s18, 0x8000
	s_addc_u32 s19, s19, 0
	s_add_u32 s78, s78, 0x8000
	s_addc_u32 s79, s79, 0
	s_add_u32 s22, s22, 0x8000
	s_addc_u32 s23, s23, 0
	s_mov_b64 vcc, s[6:7]
	v_cndmask_b32_dpp v52, v4, v0, vcc row_ror:8 row_mask:0xf bank_mask:0xf
	v_cndmask_b32_dpp v53, v5, v1, vcc row_ror:8 row_mask:0xf bank_mask:0xf
	v_cndmask_b32_dpp v54, v6, v2, vcc row_ror:8 row_mask:0xf bank_mask:0xf
	v_cndmask_b32_dpp v55, v7, v3, vcc row_ror:8 row_mask:0xf bank_mask:0xf
	v_cndmask_b32_dpp v44, v250, v246, vcc row_ror:8 row_mask:0xf bank_mask:0xf
	v_cndmask_b32_dpp v45, v251, v247, vcc row_ror:8 row_mask:0xf bank_mask:0xf
	v_cndmask_b32_dpp v46, v208, v248, vcc row_ror:8 row_mask:0xf bank_mask:0xf
	v_cndmask_b32_dpp v47, v209, v249, vcc row_ror:8 row_mask:0xf bank_mask:0xf
	s_not_b64 vcc, s[6:7]
	v_cndmask_b32_dpp v48, v0, v4, vcc row_ror:8 row_mask:0xf bank_mask:0xf
	v_cndmask_b32_dpp v49, v1, v5, vcc row_ror:8 row_mask:0xf bank_mask:0xf
	v_cndmask_b32_dpp v50, v2, v6, vcc row_ror:8 row_mask:0xf bank_mask:0xf
	v_cndmask_b32_dpp v51, v3, v7, vcc row_ror:8 row_mask:0xf bank_mask:0xf
	v_cndmask_b32_dpp v40, v246, v250, vcc row_ror:8 row_mask:0xf bank_mask:0xf
	v_cndmask_b32_dpp v41, v247, v251, vcc row_ror:8 row_mask:0xf bank_mask:0xf
	v_cndmask_b32_dpp v42, v248, v208, vcc row_ror:8 row_mask:0xf bank_mask:0xf
	v_cndmask_b32_dpp v43, v249, v209, vcc row_ror:8 row_mask:0xf bank_mask:0xf
	global_store_dwordx4 v171, v[52:55], s[2:3]
	global_store_dwordx4 v171, v[48:51], s[18:19]
	global_store_dwordx4 v171, v[44:47], s[78:79]
	global_store_dwordx4 v171, v[40:43], s[22:23]
	s_waitcnt vmcnt(14)
	s_mov_b64 vcc, s[6:7]
	v_cndmask_b32_dpp v0, v200, v196, vcc row_ror:8 row_mask:0xf bank_mask:0xf
	v_cndmask_b32_dpp v1, v201, v197, vcc row_ror:8 row_mask:0xf bank_mask:0xf
	v_cndmask_b32_dpp v2, v202, v198, vcc row_ror:8 row_mask:0xf bank_mask:0xf
	v_cndmask_b32_dpp v3, v203, v199, vcc row_ror:8 row_mask:0xf bank_mask:0xf
	s_not_b64 vcc, s[6:7]
	v_cndmask_b32_dpp v4, v196, v200, vcc row_ror:8 row_mask:0xf bank_mask:0xf
	v_cndmask_b32_dpp v5, v197, v201, vcc row_ror:8 row_mask:0xf bank_mask:0xf
	v_cndmask_b32_dpp v6, v198, v202, vcc row_ror:8 row_mask:0xf bank_mask:0xf
	v_cndmask_b32_dpp v7, v199, v203, vcc row_ror:8 row_mask:0xf bank_mask:0xf
	v_lshlrev_b32_e32 v246, 16, v0
	v_and_b32_e32 v247, 0xffff0000, v0
	v_pk_fma_f32 v[36:37], v[36:37], v[142:143], v[246:247]
	v_lshlrev_b32_e32 v248, 16, v1
	v_and_b32_e32 v249, 0xffff0000, v1
	v_pk_fma_f32 v[38:39], v[38:39], v[144:145], v[248:249]
	v_lshlrev_b32_e32 v250, 16, v2
	v_and_b32_e32 v251, 0xffff0000, v2
	v_pk_fma_f32 v[32:33], v[32:33], v[150:151], v[250:251]
	v_lshlrev_b32_e32 v208, 16, v3
	v_and_b32_e32 v209, 0xffff0000, v3
	v_pk_fma_f32 v[34:35], v[34:35], v[152:153], v[208:209]
	v_lshlrev_b32_e32 v246, 16, v4
	v_and_b32_e32 v247, 0xffff0000, v4
	v_pk_fma_f32 v[28:29], v[28:29], v[138:139], v[246:247]
	v_lshlrev_b32_e32 v248, 16, v5
	v_and_b32_e32 v249, 0xffff0000, v5
	v_pk_fma_f32 v[30:31], v[30:31], v[140:141], v[248:249]
	v_lshlrev_b32_e32 v250, 16, v6
	v_and_b32_e32 v251, 0xffff0000, v6
	v_pk_fma_f32 v[24:25], v[24:25], v[146:147], v[250:251]
	v_lshlrev_b32_e32 v208, 16, v7
	v_and_b32_e32 v209, 0xffff0000, v7
	v_pk_fma_f32 v[26:27], v[26:27], v[148:149], v[208:209]
	v_cvt_pk_bf16_f32 v0, v36, v37
	v_cvt_pk_bf16_f32 v1, v38, v39
	v_cvt_pk_bf16_f32 v2, v32, v33
	v_cvt_pk_bf16_f32 v3, v34, v35
	v_cvt_pk_bf16_f32 v4, v28, v29
	v_cvt_pk_bf16_f32 v5, v30, v31
	v_cvt_pk_bf16_f32 v6, v24, v25
	v_cvt_pk_bf16_f32 v7, v26, v27
	v_mul_f32_e32 v246, v37, v37
	v_mul_f32_e32 v248, v39, v39
	v_fmac_f32_e32 v246, v36, v36
	v_fmac_f32_e32 v248, v38, v38
	v_add_f32_e32 v246, v246, v248
	v_mul_f32_e32 v248, v33, v33
	v_fmac_f32_e32 v248, v32, v32
	v_add_f32_e32 v246, v246, v248
	v_mul_f32_e32 v248, v35, v35
	v_fmac_f32_e32 v248, v34, v34
	v_add_f32_e32 v246, v248, v246
	v_mul_f32_e32 v247, v29, v29
	v_mul_f32_e32 v248, v31, v31
	v_fmac_f32_e32 v247, v28, v28
	v_fmac_f32_e32 v248, v30, v30
	v_add_f32_e32 v247, v247, v248
	v_mul_f32_e32 v248, v25, v25
	v_fmac_f32_e32 v248, v24, v24
	v_add_f32_e32 v247, v247, v248
	v_mul_f32_e32 v248, v27, v27
	v_fmac_f32_e32 v248, v26, v26
	v_add_f32_e32 v247, v248, v247
	v_add_f32_e32 v246, v246, v247
	v_mov_b32_e32 v247, v246
	s_nop 1
	v_permlane16_swap_b32_e32 v246, v247
	s_nop 1
	v_add_f32_e32 v246, v246, v247
	v_mov_b32_e32 v247, v246
	s_nop 1
	v_permlane32_swap_b32_e32 v246, v247
	v_add_u32_e32 v248, s8, v223
	s_nop 0
	v_add_f32_e32 v246, v246, v247
	s_mov_b64 exec, s[44:45]
	ds_write_b32 v248, v246 offset:2560
	s_mov_b64 exec, -1
	v_pk_mul_f32 v[36:37], v[180:181], v[36:37]
	v_pk_mul_f32 v[38:39], v[182:183], v[38:39]
	v_pk_mul_f32 v[32:33], v[184:185], v[32:33]
	v_pk_mul_f32 v[34:35], v[186:187], v[34:35]
	v_pk_mul_f32 v[28:29], v[188:189], v[28:29]
	v_pk_mul_f32 v[30:31], v[190:191], v[30:31]
	v_pk_mul_f32 v[24:25], v[192:193], v[24:25]
	v_pk_mul_f32 v[26:27], v[194:195], v[26:27]
	v_cvt_pk_bf16_f32 v246, v36, v37
	v_cvt_pk_bf16_f32 v247, v38, v39
	v_cvt_pk_bf16_f32 v248, v32, v33
	v_cvt_pk_bf16_f32 v249, v34, v35
	v_cvt_pk_bf16_f32 v250, v28, v29
	v_cvt_pk_bf16_f32 v251, v30, v31
	v_cvt_pk_bf16_f32 v208, v24, v25
	v_cvt_pk_bf16_f32 v209, v26, v27
	s_add_u32 s2, s2, 0x8000
	s_addc_u32 s3, s3, 0
	s_add_u32 s18, s18, 0x8000
	s_addc_u32 s19, s19, 0
	s_add_u32 s78, s78, 0x8000
	s_addc_u32 s79, s79, 0
	s_add_u32 s22, s22, 0x8000
	s_addc_u32 s23, s23, 0
	s_mov_b64 vcc, s[6:7]
	v_cndmask_b32_dpp v36, v4, v0, vcc row_ror:8 row_mask:0xf bank_mask:0xf
	v_cndmask_b32_dpp v37, v5, v1, vcc row_ror:8 row_mask:0xf bank_mask:0xf
	v_cndmask_b32_dpp v38, v6, v2, vcc row_ror:8 row_mask:0xf bank_mask:0xf
	v_cndmask_b32_dpp v39, v7, v3, vcc row_ror:8 row_mask:0xf bank_mask:0xf
	v_cndmask_b32_dpp v28, v250, v246, vcc row_ror:8 row_mask:0xf bank_mask:0xf
	v_cndmask_b32_dpp v29, v251, v247, vcc row_ror:8 row_mask:0xf bank_mask:0xf
	v_cndmask_b32_dpp v30, v208, v248, vcc row_ror:8 row_mask:0xf bank_mask:0xf
	v_cndmask_b32_dpp v31, v209, v249, vcc row_ror:8 row_mask:0xf bank_mask:0xf
	s_not_b64 vcc, s[6:7]
	v_cndmask_b32_dpp v32, v0, v4, vcc row_ror:8 row_mask:0xf bank_mask:0xf
	v_cndmask_b32_dpp v33, v1, v5, vcc row_ror:8 row_mask:0xf bank_mask:0xf
	v_cndmask_b32_dpp v34, v2, v6, vcc row_ror:8 row_mask:0xf bank_mask:0xf
	v_cndmask_b32_dpp v35, v3, v7, vcc row_ror:8 row_mask:0xf bank_mask:0xf
	v_cndmask_b32_dpp v24, v246, v250, vcc row_ror:8 row_mask:0xf bank_mask:0xf
	v_cndmask_b32_dpp v25, v247, v251, vcc row_ror:8 row_mask:0xf bank_mask:0xf
	v_cndmask_b32_dpp v26, v248, v208, vcc row_ror:8 row_mask:0xf bank_mask:0xf
	v_cndmask_b32_dpp v27, v249, v209, vcc row_ror:8 row_mask:0xf bank_mask:0xf
	global_store_dwordx4 v171, v[36:39], s[2:3]
	global_store_dwordx4 v171, v[32:35], s[18:19]
	global_store_dwordx4 v171, v[28:31], s[78:79]
	global_store_dwordx4 v171, v[24:27], s[22:23]
	s_waitcnt vmcnt(12)
	s_mov_b64 vcc, s[6:7]
	v_cndmask_b32_dpp v0, v234, v204, vcc row_ror:8 row_mask:0xf bank_mask:0xf
	v_cndmask_b32_dpp v1, v235, v205, vcc row_ror:8 row_mask:0xf bank_mask:0xf
	v_cndmask_b32_dpp v2, v236, v206, vcc row_ror:8 row_mask:0xf bank_mask:0xf
	v_cndmask_b32_dpp v3, v237, v207, vcc row_ror:8 row_mask:0xf bank_mask:0xf
	s_not_b64 vcc, s[6:7]
	v_cndmask_b32_dpp v4, v204, v234, vcc row_ror:8 row_mask:0xf bank_mask:0xf
	v_cndmask_b32_dpp v5, v205, v235, vcc row_ror:8 row_mask:0xf bank_mask:0xf
	v_cndmask_b32_dpp v6, v206, v236, vcc row_ror:8 row_mask:0xf bank_mask:0xf
	v_cndmask_b32_dpp v7, v207, v237, vcc row_ror:8 row_mask:0xf bank_mask:0xf
	v_lshlrev_b32_e32 v246, 16, v0
	v_and_b32_e32 v247, 0xffff0000, v0
	v_pk_fma_f32 v[20:21], v[20:21], v[142:143], v[246:247]
	v_lshlrev_b32_e32 v248, 16, v1
	v_and_b32_e32 v249, 0xffff0000, v1
	v_pk_fma_f32 v[22:23], v[22:23], v[144:145], v[248:249]
	v_lshlrev_b32_e32 v250, 16, v2
	v_and_b32_e32 v251, 0xffff0000, v2
	v_pk_fma_f32 v[16:17], v[16:17], v[150:151], v[250:251]
	v_lshlrev_b32_e32 v208, 16, v3
	v_and_b32_e32 v209, 0xffff0000, v3
	v_pk_fma_f32 v[18:19], v[18:19], v[152:153], v[208:209]
	v_lshlrev_b32_e32 v246, 16, v4
	v_and_b32_e32 v247, 0xffff0000, v4
	v_pk_fma_f32 v[12:13], v[12:13], v[138:139], v[246:247]
	v_lshlrev_b32_e32 v248, 16, v5
	v_and_b32_e32 v249, 0xffff0000, v5
	v_pk_fma_f32 v[14:15], v[14:15], v[140:141], v[248:249]
	v_lshlrev_b32_e32 v250, 16, v6
	v_and_b32_e32 v251, 0xffff0000, v6
	v_pk_fma_f32 v[8:9], v[8:9], v[146:147], v[250:251]
	v_lshlrev_b32_e32 v208, 16, v7
	v_and_b32_e32 v209, 0xffff0000, v7
	v_pk_fma_f32 v[10:11], v[10:11], v[148:149], v[208:209]
	v_cvt_pk_bf16_f32 v0, v20, v21
	v_cvt_pk_bf16_f32 v1, v22, v23
	v_cvt_pk_bf16_f32 v2, v16, v17
	v_cvt_pk_bf16_f32 v3, v18, v19
	v_cvt_pk_bf16_f32 v4, v12, v13
	v_cvt_pk_bf16_f32 v5, v14, v15
	v_cvt_pk_bf16_f32 v6, v8, v9
	v_cvt_pk_bf16_f32 v7, v10, v11
	v_mul_f32_e32 v246, v21, v21
	v_mul_f32_e32 v248, v23, v23
	v_fmac_f32_e32 v246, v20, v20
	v_fmac_f32_e32 v248, v22, v22
	v_add_f32_e32 v246, v246, v248
	v_mul_f32_e32 v248, v17, v17
	v_fmac_f32_e32 v248, v16, v16
	v_add_f32_e32 v246, v246, v248
	v_mul_f32_e32 v248, v19, v19
	v_fmac_f32_e32 v248, v18, v18
	v_add_f32_e32 v246, v248, v246
	v_mul_f32_e32 v247, v13, v13
	v_mul_f32_e32 v248, v15, v15
	v_fmac_f32_e32 v247, v12, v12
	v_fmac_f32_e32 v248, v14, v14
	v_add_f32_e32 v247, v247, v248
	v_mul_f32_e32 v248, v9, v9
	v_fmac_f32_e32 v248, v8, v8
	v_add_f32_e32 v247, v247, v248
	v_mul_f32_e32 v248, v11, v11
	v_fmac_f32_e32 v248, v10, v10
	v_add_f32_e32 v247, v248, v247
	v_add_f32_e32 v246, v246, v247
	v_mov_b32_e32 v247, v246
	s_nop 1
	v_permlane16_swap_b32_e32 v246, v247
	s_nop 1
	v_add_f32_e32 v246, v246, v247
	v_mov_b32_e32 v247, v246
	s_nop 1
	v_permlane32_swap_b32_e32 v246, v247
	v_add_u32_e32 v248, s8, v223
	s_nop 0
	v_add_f32_e32 v246, v246, v247
	s_mov_b64 exec, s[44:45]
	ds_write_b32 v248, v246 offset:2816
	s_mov_b64 exec, -1
	v_pk_mul_f32 v[20:21], v[180:181], v[20:21]
	v_pk_mul_f32 v[22:23], v[182:183], v[22:23]
	v_pk_mul_f32 v[16:17], v[184:185], v[16:17]
	v_pk_mul_f32 v[18:19], v[186:187], v[18:19]
	v_pk_mul_f32 v[12:13], v[188:189], v[12:13]
	v_pk_mul_f32 v[14:15], v[190:191], v[14:15]
	v_pk_mul_f32 v[8:9], v[192:193], v[8:9]
	v_pk_mul_f32 v[10:11], v[194:195], v[10:11]
	v_cvt_pk_bf16_f32 v246, v20, v21
	v_cvt_pk_bf16_f32 v247, v22, v23
	v_cvt_pk_bf16_f32 v248, v16, v17
	v_cvt_pk_bf16_f32 v249, v18, v19
	v_cvt_pk_bf16_f32 v250, v12, v13
	v_cvt_pk_bf16_f32 v251, v14, v15
	v_cvt_pk_bf16_f32 v208, v8, v9
	v_cvt_pk_bf16_f32 v209, v10, v11
	s_add_u32 s2, s2, 0x8000
	s_addc_u32 s3, s3, 0
	s_add_u32 s18, s18, 0x8000
	s_addc_u32 s19, s19, 0
	s_add_u32 s78, s78, 0x8000
	s_addc_u32 s79, s79, 0
	s_add_u32 s22, s22, 0x8000
	s_addc_u32 s23, s23, 0
	s_mov_b64 vcc, s[6:7]
	v_cndmask_b32_dpp v20, v4, v0, vcc row_ror:8 row_mask:0xf bank_mask:0xf
	v_cndmask_b32_dpp v21, v5, v1, vcc row_ror:8 row_mask:0xf bank_mask:0xf
	v_cndmask_b32_dpp v22, v6, v2, vcc row_ror:8 row_mask:0xf bank_mask:0xf
	v_cndmask_b32_dpp v23, v7, v3, vcc row_ror:8 row_mask:0xf bank_mask:0xf
	v_cndmask_b32_dpp v12, v250, v246, vcc row_ror:8 row_mask:0xf bank_mask:0xf
	v_cndmask_b32_dpp v13, v251, v247, vcc row_ror:8 row_mask:0xf bank_mask:0xf
	v_cndmask_b32_dpp v14, v208, v248, vcc row_ror:8 row_mask:0xf bank_mask:0xf
	v_cndmask_b32_dpp v15, v209, v249, vcc row_ror:8 row_mask:0xf bank_mask:0xf
	s_not_b64 vcc, s[6:7]
	v_cndmask_b32_dpp v16, v0, v4, vcc row_ror:8 row_mask:0xf bank_mask:0xf
	v_cndmask_b32_dpp v17, v1, v5, vcc row_ror:8 row_mask:0xf bank_mask:0xf
	v_cndmask_b32_dpp v18, v2, v6, vcc row_ror:8 row_mask:0xf bank_mask:0xf
	v_cndmask_b32_dpp v19, v3, v7, vcc row_ror:8 row_mask:0xf bank_mask:0xf
	v_cndmask_b32_dpp v8, v246, v250, vcc row_ror:8 row_mask:0xf bank_mask:0xf
	v_cndmask_b32_dpp v9, v247, v251, vcc row_ror:8 row_mask:0xf bank_mask:0xf
	v_cndmask_b32_dpp v10, v248, v208, vcc row_ror:8 row_mask:0xf bank_mask:0xf
	v_cndmask_b32_dpp v11, v249, v209, vcc row_ror:8 row_mask:0xf bank_mask:0xf
	global_store_dwordx4 v171, v[20:23], s[2:3]
	global_store_dwordx4 v171, v[16:19], s[18:19]
	global_store_dwordx4 v171, v[12:15], s[78:79]
	global_store_dwordx4 v171, v[8:11], s[22:23]
	s_branch .LBB0_714
.Lfo_nong:
	global_load_dwordx4 v[142:145], v170, s[16:17]
	global_load_dwordx4 v[150:153], v170, s[16:17] offset:16
	global_load_dwordx4 v[138:141], v170, s[16:17] offset:128
	global_load_dwordx4 v[146:149], v170, s[16:17] offset:144
	global_load_dwordx4 v[196:199], v171, s[14:15]
	global_load_dwordx4 v[200:203], v171, s[12:13]
	s_add_u32 s14, s14, 0x8000
	s_addc_u32 s15, s15, 0
	s_add_u32 s12, s12, 0x8000
	s_addc_u32 s13, s13, 0
	global_load_dwordx4 v[204:207], v171, s[14:15]
	global_load_dwordx4 v[234:237], v171, s[12:13]
	s_add_u32 s14, s14, 0x8000
	s_addc_u32 s15, s15, 0
	s_add_u32 s12, s12, 0x8000
	s_addc_u32 s13, s13, 0
	global_load_dwordx4 v[238:241], v171, s[14:15]
	global_load_dwordx4 v[242:245], v171, s[12:13]
	s_waitcnt vmcnt(4)
	s_mov_b64 vcc, s[6:7]
	v_cndmask_b32_dpp v0, v200, v196, vcc row_ror:8 row_mask:0xf bank_mask:0xf
	v_cndmask_b32_dpp v1, v201, v197, vcc row_ror:8 row_mask:0xf bank_mask:0xf
	v_cndmask_b32_dpp v2, v202, v198, vcc row_ror:8 row_mask:0xf bank_mask:0xf
	v_cndmask_b32_dpp v3, v203, v199, vcc row_ror:8 row_mask:0xf bank_mask:0xf
	s_not_b64 vcc, s[6:7]
	v_cndmask_b32_dpp v4, v196, v200, vcc row_ror:8 row_mask:0xf bank_mask:0xf
	v_cndmask_b32_dpp v5, v197, v201, vcc row_ror:8 row_mask:0xf bank_mask:0xf
	v_cndmask_b32_dpp v6, v198, v202, vcc row_ror:8 row_mask:0xf bank_mask:0xf
	v_cndmask_b32_dpp v7, v199, v203, vcc row_ror:8 row_mask:0xf bank_mask:0xf
	s_add_u32 s14, s14, 0x8000
	s_addc_u32 s15, s15, 0
	s_add_u32 s12, s12, 0x8000
	s_addc_u32 s13, s13, 0
	global_load_dwordx4 v[196:199], v171, s[14:15]
	global_load_dwordx4 v[200:203], v171, s[12:13]
	v_lshlrev_b32_e32 v246, 16, v0
	v_and_b32_e32 v247, 0xffff0000, v0
	v_pk_fma_f32 v[134:135], v[134:135], v[142:143], v[246:247]
	v_lshlrev_b32_e32 v248, 16, v1
	v_and_b32_e32 v249, 0xffff0000, v1
	v_pk_fma_f32 v[136:137], v[136:137], v[144:145], v[248:249]
	v_lshlrev_b32_e32 v250, 16, v2
	v_and_b32_e32 v251, 0xffff0000, v2
	v_pk_fma_f32 v[130:131], v[130:131], v[150:151], v[250:251]
	v_lshlrev_b32_e32 v208, 16, v3
	v_and_b32_e32 v209, 0xffff0000, v3
	v_pk_fma_f32 v[132:133], v[132:133], v[152:153], v[208:209]
	v_lshlrev_b32_e32 v246, 16, v4
	v_and_b32_e32 v247, 0xffff0000, v4
	v_pk_fma_f32 v[126:127], v[126:127], v[138:139], v[246:247]
	v_lshlrev_b32_e32 v248, 16, v5
	v_and_b32_e32 v249, 0xffff0000, v5
	v_pk_fma_f32 v[128:129], v[128:129], v[140:141], v[248:249]
	v_lshlrev_b32_e32 v250, 16, v6
	v_and_b32_e32 v251, 0xffff0000, v6
	v_pk_fma_f32 v[122:123], v[122:123], v[146:147], v[250:251]
	v_lshlrev_b32_e32 v208, 16, v7
	v_and_b32_e32 v209, 0xffff0000, v7
	v_pk_fma_f32 v[124:125], v[124:125], v[148:149], v[208:209]
	v_cvt_pk_bf16_f32 v0, v134, v135
	v_cvt_pk_bf16_f32 v1, v136, v137
	v_cvt_pk_bf16_f32 v2, v130, v131
	v_cvt_pk_bf16_f32 v3, v132, v133
	v_cvt_pk_bf16_f32 v4, v126, v127
	v_cvt_pk_bf16_f32 v5, v128, v129
	v_cvt_pk_bf16_f32 v6, v122, v123
	v_cvt_pk_bf16_f32 v7, v124, v125
	v_mul_f32_e32 v246, v135, v135
	v_mul_f32_e32 v248, v137, v137
	v_fmac_f32_e32 v246, v134, v134
	v_fmac_f32_e32 v248, v136, v136
	v_add_f32_e32 v246, v246, v248
	v_mul_f32_e32 v248, v131, v131
	v_fmac_f32_e32 v248, v130, v130
	v_add_f32_e32 v246, v246, v248
	v_mul_f32_e32 v248, v133, v133
	v_fmac_f32_e32 v248, v132, v132
	v_add_f32_e32 v246, v248, v246
	v_mul_f32_e32 v247, v127, v127
	v_mul_f32_e32 v248, v129, v129
	v_fmac_f32_e32 v247, v126, v126
	v_fmac_f32_e32 v248, v128, v128
	v_add_f32_e32 v247, v247, v248
	v_mul_f32_e32 v248, v123, v123
	v_fmac_f32_e32 v248, v122, v122
	v_add_f32_e32 v247, v247, v248
	v_mul_f32_e32 v248, v125, v125
	v_fmac_f32_e32 v248, v124, v124
	v_add_f32_e32 v247, v248, v247
	v_add_f32_e32 v246, v246, v247
	v_mov_b32_e32 v247, v246
	s_nop 1
	v_permlane16_swap_b32_e32 v246, v247
	s_nop 1
	v_add_f32_e32 v246, v246, v247
	v_mov_b32_e32 v247, v246
	s_nop 1
	v_permlane32_swap_b32_e32 v246, v247
	v_add_u32_e32 v248, s8, v223
	s_nop 0
	v_add_f32_e32 v246, v246, v247
	s_mov_b64 exec, s[44:45]
	ds_write_b32 v248, v246
	s_mov_b64 exec, -1
	s_nop 1
	s_mov_b64 vcc, s[6:7]
	v_cndmask_b32_dpp v134, v4, v0, vcc row_ror:8 row_mask:0xf bank_mask:0xf
	v_cndmask_b32_dpp v135, v5, v1, vcc row_ror:8 row_mask:0xf bank_mask:0xf
	v_cndmask_b32_dpp v136, v6, v2, vcc row_ror:8 row_mask:0xf bank_mask:0xf
	v_cndmask_b32_dpp v137, v7, v3, vcc row_ror:8 row_mask:0xf bank_mask:0xf
	s_not_b64 vcc, s[6:7]
	v_cndmask_b32_dpp v130, v0, v4, vcc row_ror:8 row_mask:0xf bank_mask:0xf
	v_cndmask_b32_dpp v131, v1, v5, vcc row_ror:8 row_mask:0xf bank_mask:0xf
	v_cndmask_b32_dpp v132, v2, v6, vcc row_ror:8 row_mask:0xf bank_mask:0xf
	v_cndmask_b32_dpp v133, v3, v7, vcc row_ror:8 row_mask:0xf bank_mask:0xf
	global_store_dwordx4 v171, v[134:137], s[2:3]
	global_store_dwordx4 v171, v[130:133], s[18:19]
	s_waitcnt vmcnt(6)
	s_mov_b64 vcc, s[6:7]
	v_cndmask_b32_dpp v0, v234, v204, vcc row_ror:8 row_mask:0xf bank_mask:0xf
	v_cndmask_b32_dpp v1, v235, v205, vcc row_ror:8 row_mask:0xf bank_mask:0xf
	v_cndmask_b32_dpp v2, v236, v206, vcc row_ror:8 row_mask:0xf bank_mask:0xf
	v_cndmask_b32_dpp v3, v237, v207, vcc row_ror:8 row_mask:0xf bank_mask:0xf
	s_not_b64 vcc, s[6:7]
	v_cndmask_b32_dpp v4, v204, v234, vcc row_ror:8 row_mask:0xf bank_mask:0xf
	v_cndmask_b32_dpp v5, v205, v235, vcc row_ror:8 row_mask:0xf bank_mask:0xf
	v_cndmask_b32_dpp v6, v206, v236, vcc row_ror:8 row_mask:0xf bank_mask:0xf
	v_cndmask_b32_dpp v7, v207, v237, vcc row_ror:8 row_mask:0xf bank_mask:0xf
	s_add_u32 s14, s14, 0x28000
	s_addc_u32 s15, s15, 0
	s_add_u32 s12, s12, 0x28000
	s_addc_u32 s13, s13, 0
	global_load_dwordx4 v[204:207], v171, s[14:15]
	global_load_dwordx4 v[234:237], v171, s[12:13]
	v_lshlrev_b32_e32 v246, 16, v0
	v_and_b32_e32 v247, 0xffff0000, v0
	v_pk_fma_f32 v[118:119], v[118:119], v[142:143], v[246:247]
	v_lshlrev_b32_e32 v248, 16, v1
	v_and_b32_e32 v249, 0xffff0000, v1
	v_pk_fma_f32 v[120:121], v[120:121], v[144:145], v[248:249]
	v_lshlrev_b32_e32 v250, 16, v2
	v_and_b32_e32 v251, 0xffff0000, v2
	v_pk_fma_f32 v[114:115], v[114:115], v[150:151], v[250:251]
	v_lshlrev_b32_e32 v208, 16, v3
	v_and_b32_e32 v209, 0xffff0000, v3
	v_pk_fma_f32 v[116:117], v[116:117], v[152:153], v[208:209]
	v_lshlrev_b32_e32 v246, 16, v4
	v_and_b32_e32 v247, 0xffff0000, v4
	v_pk_fma_f32 v[110:111], v[110:111], v[138:139], v[246:247]
	v_lshlrev_b32_e32 v248, 16, v5
	v_and_b32_e32 v249, 0xffff0000, v5
	v_pk_fma_f32 v[112:113], v[112:113], v[140:141], v[248:249]
	v_lshlrev_b32_e32 v250, 16, v6
	v_and_b32_e32 v251, 0xffff0000, v6
	v_pk_fma_f32 v[106:107], v[106:107], v[146:147], v[250:251]
	v_lshlrev_b32_e32 v208, 16, v7
	v_and_b32_e32 v209, 0xffff0000, v7
	v_pk_fma_f32 v[108:109], v[108:109], v[148:149], v[208:209]
	v_cvt_pk_bf16_f32 v0, v118, v119
	v_cvt_pk_bf16_f32 v1, v120, v121
	v_cvt_pk_bf16_f32 v2, v114, v115
	v_cvt_pk_bf16_f32 v3, v116, v117
	v_cvt_pk_bf16_f32 v4, v110, v111
	v_cvt_pk_bf16_f32 v5, v112, v113
	v_cvt_pk_bf16_f32 v6, v106, v107
	v_cvt_pk_bf16_f32 v7, v108, v109
	v_mul_f32_e32 v246, v119, v119
	v_mul_f32_e32 v248, v121, v121
	v_fmac_f32_e32 v246, v118, v118
	v_fmac_f32_e32 v248, v120, v120
	v_add_f32_e32 v246, v246, v248
	v_mul_f32_e32 v248, v115, v115
	v_fmac_f32_e32 v248, v114, v114
	v_add_f32_e32 v246, v246, v248
	v_mul_f32_e32 v248, v117, v117
	v_fmac_f32_e32 v248, v116, v116
	v_add_f32_e32 v246, v248, v246
	v_mul_f32_e32 v247, v111, v111
	v_mul_f32_e32 v248, v113, v113
	v_fmac_f32_e32 v247, v110, v110
	v_fmac_f32_e32 v248, v112, v112
	v_add_f32_e32 v247, v247, v248
	v_mul_f32_e32 v248, v107, v107
	v_fmac_f32_e32 v248, v106, v106
	v_add_f32_e32 v247, v247, v248
	v_mul_f32_e32 v248, v109, v109
	v_fmac_f32_e32 v248, v108, v108
	v_add_f32_e32 v247, v248, v247
	v_add_f32_e32 v246, v246, v247
	v_mov_b32_e32 v247, v246
	s_nop 1
	v_permlane16_swap_b32_e32 v246, v247
	s_nop 1
	v_add_f32_e32 v246, v246, v247
	v_mov_b32_e32 v247, v246
	s_nop 1
	v_permlane32_swap_b32_e32 v246, v247
	v_add_u32_e32 v248, s8, v223
	s_nop 0
	v_add_f32_e32 v246, v246, v247
	s_mov_b64 exec, s[44:45]
	ds_write_b32 v248, v246 offset:256
	s_mov_b64 exec, -1
	s_add_u32 s2, s2, 0x8000
	s_addc_u32 s3, s3, 0
	s_add_u32 s18, s18, 0x8000
	s_addc_u32 s19, s19, 0
	s_mov_b64 vcc, s[6:7]
	v_cndmask_b32_dpp v118, v4, v0, vcc row_ror:8 row_mask:0xf bank_mask:0xf
	v_cndmask_b32_dpp v119, v5, v1, vcc row_ror:8 row_mask:0xf bank_mask:0xf
	v_cndmask_b32_dpp v120, v6, v2, vcc row_ror:8 row_mask:0xf bank_mask:0xf
	v_cndmask_b32_dpp v121, v7, v3, vcc row_ror:8 row_mask:0xf bank_mask:0xf
	s_not_b64 vcc, s[6:7]
	v_cndmask_b32_dpp v114, v0, v4, vcc row_ror:8 row_mask:0xf bank_mask:0xf
	v_cndmask_b32_dpp v115, v1, v5, vcc row_ror:8 row_mask:0xf bank_mask:0xf
	v_cndmask_b32_dpp v116, v2, v6, vcc row_ror:8 row_mask:0xf bank_mask:0xf
	v_cndmask_b32_dpp v117, v3, v7, vcc row_ror:8 row_mask:0xf bank_mask:0xf
	global_store_dwordx4 v171, v[118:121], s[2:3]
	global_store_dwordx4 v171, v[114:117], s[18:19]
	s_waitcnt vmcnt(8)
	s_mov_b64 vcc, s[6:7]
	v_cndmask_b32_dpp v0, v242, v238, vcc row_ror:8 row_mask:0xf bank_mask:0xf
	v_cndmask_b32_dpp v1, v243, v239, vcc row_ror:8 row_mask:0xf bank_mask:0xf
	v_cndmask_b32_dpp v2, v244, v240, vcc row_ror:8 row_mask:0xf bank_mask:0xf
	v_cndmask_b32_dpp v3, v245, v241, vcc row_ror:8 row_mask:0xf bank_mask:0xf
	s_not_b64 vcc, s[6:7]
	v_cndmask_b32_dpp v4, v238, v242, vcc row_ror:8 row_mask:0xf bank_mask:0xf
	v_cndmask_b32_dpp v5, v239, v243, vcc row_ror:8 row_mask:0xf bank_mask:0xf
	v_cndmask_b32_dpp v6, v240, v244, vcc row_ror:8 row_mask:0xf bank_mask:0xf
	v_cndmask_b32_dpp v7, v241, v245, vcc row_ror:8 row_mask:0xf bank_mask:0xf
	s_add_u32 s14, s14, 0x8000
	s_addc_u32 s15, s15, 0
	s_add_u32 s12, s12, 0x8000
	s_addc_u32 s13, s13, 0
	global_load_dwordx4 v[238:241], v171, s[14:15]
	global_load_dwordx4 v[242:245], v171, s[12:13]
	v_lshlrev_b32_e32 v246, 16, v0
	v_and_b32_e32 v247, 0xffff0000, v0
	v_pk_fma_f32 v[102:103], v[102:103], v[142:143], v[246:247]
	v_lshlrev_b32_e32 v248, 16, v1
	v_and_b32_e32 v249, 0xffff0000, v1
	v_pk_fma_f32 v[104:105], v[104:105], v[144:145], v[248:249]
	v_lshlrev_b32_e32 v250, 16, v2
	v_and_b32_e32 v251, 0xffff0000, v2
	v_pk_fma_f32 v[98:99], v[98:99], v[150:151], v[250:251]
	v_lshlrev_b32_e32 v208, 16, v3
	v_and_b32_e32 v209, 0xffff0000, v3
	v_pk_fma_f32 v[100:101], v[100:101], v[152:153], v[208:209]
	v_lshlrev_b32_e32 v246, 16, v4
	v_and_b32_e32 v247, 0xffff0000, v4
	v_pk_fma_f32 v[92:93], v[92:93], v[138:139], v[246:247]
	v_lshlrev_b32_e32 v248, 16, v5
	v_and_b32_e32 v249, 0xffff0000, v5
	v_pk_fma_f32 v[94:95], v[94:95], v[140:141], v[248:249]
	v_lshlrev_b32_e32 v250, 16, v6
	v_and_b32_e32 v251, 0xffff0000, v6
	v_pk_fma_f32 v[88:89], v[88:89], v[146:147], v[250:251]
	v_lshlrev_b32_e32 v208, 16, v7
	v_and_b32_e32 v209, 0xffff0000, v7
	v_pk_fma_f32 v[90:91], v[90:91], v[148:149], v[208:209]
	v_cvt_pk_bf16_f32 v0, v102, v103
	v_cvt_pk_bf16_f32 v1, v104, v105
	v_cvt_pk_bf16_f32 v2, v98, v99
	v_cvt_pk_bf16_f32 v3, v100, v101
	v_cvt_pk_bf16_f32 v4, v92, v93
	v_cvt_pk_bf16_f32 v5, v94, v95
	v_cvt_pk_bf16_f32 v6, v88, v89
	v_cvt_pk_bf16_f32 v7, v90, v91
	v_mul_f32_e32 v246, v103, v103
	v_mul_f32_e32 v248, v105, v105
	v_fmac_f32_e32 v246, v102, v102
	v_fmac_f32_e32 v248, v104, v104
	v_add_f32_e32 v246, v246, v248
	v_mul_f32_e32 v248, v99, v99
	v_fmac_f32_e32 v248, v98, v98
	v_add_f32_e32 v246, v246, v248
	v_mul_f32_e32 v248, v101, v101
	v_fmac_f32_e32 v248, v100, v100
	v_add_f32_e32 v246, v248, v246
	v_mul_f32_e32 v247, v93, v93
	v_mul_f32_e32 v248, v95, v95
	v_fmac_f32_e32 v247, v92, v92
	v_fmac_f32_e32 v248, v94, v94
	v_add_f32_e32 v247, v247, v248
	v_mul_f32_e32 v248, v89, v89
	v_fmac_f32_e32 v248, v88, v88
	v_add_f32_e32 v247, v247, v248
	v_mul_f32_e32 v248, v91, v91
	v_fmac_f32_e32 v248, v90, v90
	v_add_f32_e32 v247, v248, v247
	v_add_f32_e32 v246, v246, v247
	v_mov_b32_e32 v247, v246
	s_nop 1
	v_permlane16_swap_b32_e32 v246, v247
	s_nop 1
	v_add_f32_e32 v246, v246, v247
	v_mov_b32_e32 v247, v246
	s_nop 1
	v_permlane32_swap_b32_e32 v246, v247
	v_add_u32_e32 v248, s8, v223
	s_nop 0
	v_add_f32_e32 v246, v246, v247
	s_mov_b64 exec, s[44:45]
	ds_write_b32 v248, v246 offset:512
	s_mov_b64 exec, -1
	s_add_u32 s2, s2, 0x8000
	s_addc_u32 s3, s3, 0
	s_add_u32 s18, s18, 0x8000
	s_addc_u32 s19, s19, 0
	s_mov_b64 vcc, s[6:7]
	v_cndmask_b32_dpp v102, v4, v0, vcc row_ror:8 row_mask:0xf bank_mask:0xf
	v_cndmask_b32_dpp v103, v5, v1, vcc row_ror:8 row_mask:0xf bank_mask:0xf
	v_cndmask_b32_dpp v104, v6, v2, vcc row_ror:8 row_mask:0xf bank_mask:0xf
	v_cndmask_b32_dpp v105, v7, v3, vcc row_ror:8 row_mask:0xf bank_mask:0xf
	s_not_b64 vcc, s[6:7]
	v_cndmask_b32_dpp v98, v0, v4, vcc row_ror:8 row_mask:0xf bank_mask:0xf
	v_cndmask_b32_dpp v99, v1, v5, vcc row_ror:8 row_mask:0xf bank_mask:0xf
	v_cndmask_b32_dpp v100, v2, v6, vcc row_ror:8 row_mask:0xf bank_mask:0xf
	v_cndmask_b32_dpp v101, v3, v7, vcc row_ror:8 row_mask:0xf bank_mask:0xf
	global_store_dwordx4 v171, v[102:105], s[2:3]
	global_store_dwordx4 v171, v[98:101], s[18:19]
	s_waitcnt vmcnt(10)
	s_mov_b64 vcc, s[6:7]
	v_cndmask_b32_dpp v0, v200, v196, vcc row_ror:8 row_mask:0xf bank_mask:0xf
	v_cndmask_b32_dpp v1, v201, v197, vcc row_ror:8 row_mask:0xf bank_mask:0xf
	v_cndmask_b32_dpp v2, v202, v198, vcc row_ror:8 row_mask:0xf bank_mask:0xf
	v_cndmask_b32_dpp v3, v203, v199, vcc row_ror:8 row_mask:0xf bank_mask:0xf
	s_not_b64 vcc, s[6:7]
	v_cndmask_b32_dpp v4, v196, v200, vcc row_ror:8 row_mask:0xf bank_mask:0xf
	v_cndmask_b32_dpp v5, v197, v201, vcc row_ror:8 row_mask:0xf bank_mask:0xf
	v_cndmask_b32_dpp v6, v198, v202, vcc row_ror:8 row_mask:0xf bank_mask:0xf
	v_cndmask_b32_dpp v7, v199, v203, vcc row_ror:8 row_mask:0xf bank_mask:0xf
	s_add_u32 s14, s14, 0x8000
	s_addc_u32 s15, s15, 0
	s_add_u32 s12, s12, 0x8000
	s_addc_u32 s13, s13, 0
	global_load_dwordx4 v[196:199], v171, s[14:15]
	global_load_dwordx4 v[200:203], v171, s[12:13]
	v_lshlrev_b32_e32 v246, 16, v0
	v_and_b32_e32 v247, 0xffff0000, v0
	v_pk_fma_f32 v[84:85], v[84:85], v[142:143], v[246:247]
	v_lshlrev_b32_e32 v248, 16, v1
	v_and_b32_e32 v249, 0xffff0000, v1
	v_pk_fma_f32 v[86:87], v[86:87], v[144:145], v[248:249]
	v_lshlrev_b32_e32 v250, 16, v2
	v_and_b32_e32 v251, 0xffff0000, v2
	v_pk_fma_f32 v[80:81], v[80:81], v[150:151], v[250:251]
	v_lshlrev_b32_e32 v208, 16, v3
	v_and_b32_e32 v209, 0xffff0000, v3
	v_pk_fma_f32 v[82:83], v[82:83], v[152:153], v[208:209]
	v_lshlrev_b32_e32 v246, 16, v4
	v_and_b32_e32 v247, 0xffff0000, v4
	v_pk_fma_f32 v[76:77], v[76:77], v[138:139], v[246:247]
	v_lshlrev_b32_e32 v248, 16, v5
	v_and_b32_e32 v249, 0xffff0000, v5
	v_pk_fma_f32 v[78:79], v[78:79], v[140:141], v[248:249]
	v_lshlrev_b32_e32 v250, 16, v6
	v_and_b32_e32 v251, 0xffff0000, v6
	v_pk_fma_f32 v[72:73], v[72:73], v[146:147], v[250:251]
	v_lshlrev_b32_e32 v208, 16, v7
	v_and_b32_e32 v209, 0xffff0000, v7
	v_pk_fma_f32 v[74:75], v[74:75], v[148:149], v[208:209]
	v_cvt_pk_bf16_f32 v0, v84, v85
	v_cvt_pk_bf16_f32 v1, v86, v87
	v_cvt_pk_bf16_f32 v2, v80, v81
	v_cvt_pk_bf16_f32 v3, v82, v83
	v_cvt_pk_bf16_f32 v4, v76, v77
	v_cvt_pk_bf16_f32 v5, v78, v79
	v_cvt_pk_bf16_f32 v6, v72, v73
	v_cvt_pk_bf16_f32 v7, v74, v75
	v_mul_f32_e32 v246, v85, v85
	v_mul_f32_e32 v248, v87, v87
	v_fmac_f32_e32 v246, v84, v84
	v_fmac_f32_e32 v248, v86, v86
	v_add_f32_e32 v246, v246, v248
	v_mul_f32_e32 v248, v81, v81
	v_fmac_f32_e32 v248, v80, v80
	v_add_f32_e32 v246, v246, v248
	v_mul_f32_e32 v248, v83, v83
	v_fmac_f32_e32 v248, v82, v82
	v_add_f32_e32 v246, v248, v246
	v_mul_f32_e32 v247, v77, v77
	v_mul_f32_e32 v248, v79, v79
	v_fmac_f32_e32 v247, v76, v76
	v_fmac_f32_e32 v248, v78, v78
	v_add_f32_e32 v247, v247, v248
	v_mul_f32_e32 v248, v73, v73
	v_fmac_f32_e32 v248, v72, v72
	v_add_f32_e32 v247, v247, v248
	v_mul_f32_e32 v248, v75, v75
	v_fmac_f32_e32 v248, v74, v74
	v_add_f32_e32 v247, v248, v247
	v_add_f32_e32 v246, v246, v247
	v_mov_b32_e32 v247, v246
	s_nop 1
	v_permlane16_swap_b32_e32 v246, v247
	s_nop 1
	v_add_f32_e32 v246, v246, v247
	v_mov_b32_e32 v247, v246
	s_nop 1
	v_permlane32_swap_b32_e32 v246, v247
	v_add_u32_e32 v248, s8, v223
	s_nop 0
	v_add_f32_e32 v246, v246, v247
	s_mov_b64 exec, s[44:45]
	ds_write_b32 v248, v246 offset:768
	s_mov_b64 exec, -1
	s_add_u32 s2, s2, 0x8000
	s_addc_u32 s3, s3, 0
	s_add_u32 s18, s18, 0x8000
	s_addc_u32 s19, s19, 0
	s_mov_b64 vcc, s[6:7]
	v_cndmask_b32_dpp v84, v4, v0, vcc row_ror:8 row_mask:0xf bank_mask:0xf
	v_cndmask_b32_dpp v85, v5, v1, vcc row_ror:8 row_mask:0xf bank_mask:0xf
	v_cndmask_b32_dpp v86, v6, v2, vcc row_ror:8 row_mask:0xf bank_mask:0xf
	v_cndmask_b32_dpp v87, v7, v3, vcc row_ror:8 row_mask:0xf bank_mask:0xf
	s_not_b64 vcc, s[6:7]
	v_cndmask_b32_dpp v80, v0, v4, vcc row_ror:8 row_mask:0xf bank_mask:0xf
	v_cndmask_b32_dpp v81, v1, v5, vcc row_ror:8 row_mask:0xf bank_mask:0xf
	v_cndmask_b32_dpp v82, v2, v6, vcc row_ror:8 row_mask:0xf bank_mask:0xf
	v_cndmask_b32_dpp v83, v3, v7, vcc row_ror:8 row_mask:0xf bank_mask:0xf
	global_store_dwordx4 v171, v[84:87], s[2:3]
	global_store_dwordx4 v171, v[80:83], s[18:19]
	s_waitcnt vmcnt(10)
	s_mov_b64 vcc, s[6:7]
	v_cndmask_b32_dpp v0, v234, v204, vcc row_ror:8 row_mask:0xf bank_mask:0xf
	v_cndmask_b32_dpp v1, v235, v205, vcc row_ror:8 row_mask:0xf bank_mask:0xf
	v_cndmask_b32_dpp v2, v236, v206, vcc row_ror:8 row_mask:0xf bank_mask:0xf
	v_cndmask_b32_dpp v3, v237, v207, vcc row_ror:8 row_mask:0xf bank_mask:0xf
	s_not_b64 vcc, s[6:7]
	v_cndmask_b32_dpp v4, v204, v234, vcc row_ror:8 row_mask:0xf bank_mask:0xf
	v_cndmask_b32_dpp v5, v205, v235, vcc row_ror:8 row_mask:0xf bank_mask:0xf
	v_cndmask_b32_dpp v6, v206, v236, vcc row_ror:8 row_mask:0xf bank_mask:0xf
	v_cndmask_b32_dpp v7, v207, v237, vcc row_ror:8 row_mask:0xf bank_mask:0xf
	s_add_u32 s14, s14, 0x8000
	s_addc_u32 s15, s15, 0
	s_add_u32 s12, s12, 0x8000
	s_addc_u32 s13, s13, 0
	global_load_dwordx4 v[204:207], v171, s[14:15]
	global_load_dwordx4 v[234:237], v171, s[12:13]
	v_lshlrev_b32_e32 v246, 16, v0
	v_and_b32_e32 v247, 0xffff0000, v0
	v_pk_fma_f32 v[68:69], v[68:69], v[142:143], v[246:247]
	v_lshlrev_b32_e32 v248, 16, v1
	v_and_b32_e32 v249, 0xffff0000, v1
	v_pk_fma_f32 v[70:71], v[70:71], v[144:145], v[248:249]
	v_lshlrev_b32_e32 v250, 16, v2
	v_and_b32_e32 v251, 0xffff0000, v2
	v_pk_fma_f32 v[64:65], v[64:65], v[150:151], v[250:251]
	v_lshlrev_b32_e32 v208, 16, v3
	v_and_b32_e32 v209, 0xffff0000, v3
	v_pk_fma_f32 v[66:67], v[66:67], v[152:153], v[208:209]
	v_lshlrev_b32_e32 v246, 16, v4
	v_and_b32_e32 v247, 0xffff0000, v4
	v_pk_fma_f32 v[60:61], v[60:61], v[138:139], v[246:247]
	v_lshlrev_b32_e32 v248, 16, v5
	v_and_b32_e32 v249, 0xffff0000, v5
	v_pk_fma_f32 v[62:63], v[62:63], v[140:141], v[248:249]
	v_lshlrev_b32_e32 v250, 16, v6
	v_and_b32_e32 v251, 0xffff0000, v6
	v_pk_fma_f32 v[56:57], v[56:57], v[146:147], v[250:251]
	v_lshlrev_b32_e32 v208, 16, v7
	v_and_b32_e32 v209, 0xffff0000, v7
	v_pk_fma_f32 v[58:59], v[58:59], v[148:149], v[208:209]
	v_cvt_pk_bf16_f32 v0, v68, v69
	v_cvt_pk_bf16_f32 v1, v70, v71
	v_cvt_pk_bf16_f32 v2, v64, v65
	v_cvt_pk_bf16_f32 v3, v66, v67
	v_cvt_pk_bf16_f32 v4, v60, v61
	v_cvt_pk_bf16_f32 v5, v62, v63
	v_cvt_pk_bf16_f32 v6, v56, v57
	v_cvt_pk_bf16_f32 v7, v58, v59
	v_mul_f32_e32 v246, v69, v69
	v_mul_f32_e32 v248, v71, v71
	v_fmac_f32_e32 v246, v68, v68
	v_fmac_f32_e32 v248, v70, v70
	v_add_f32_e32 v246, v246, v248
	v_mul_f32_e32 v248, v65, v65
	v_fmac_f32_e32 v248, v64, v64
	v_add_f32_e32 v246, v246, v248
	v_mul_f32_e32 v248, v67, v67
	v_fmac_f32_e32 v248, v66, v66
	v_add_f32_e32 v246, v248, v246
	v_mul_f32_e32 v247, v61, v61
	v_mul_f32_e32 v248, v63, v63
	v_fmac_f32_e32 v247, v60, v60
	v_fmac_f32_e32 v248, v62, v62
	v_add_f32_e32 v247, v247, v248
	v_mul_f32_e32 v248, v57, v57
	v_fmac_f32_e32 v248, v56, v56
	v_add_f32_e32 v247, v247, v248
	v_mul_f32_e32 v248, v59, v59
	v_fmac_f32_e32 v248, v58, v58
	v_add_f32_e32 v247, v248, v247
	v_add_f32_e32 v246, v246, v247
	v_mov_b32_e32 v247, v246
	s_nop 1
	v_permlane16_swap_b32_e32 v246, v247
	s_nop 1
	v_add_f32_e32 v246, v246, v247
	v_mov_b32_e32 v247, v246
	s_nop 1
	v_permlane32_swap_b32_e32 v246, v247
	v_add_u32_e32 v248, s8, v223
	s_nop 0
	v_add_f32_e32 v246, v246, v247
	s_mov_b64 exec, s[44:45]
	ds_write_b32 v248, v246 offset:2048
	s_mov_b64 exec, -1
	s_add_u32 s2, s2, 0x28000
	s_addc_u32 s3, s3, 0
	s_add_u32 s18, s18, 0x28000
	s_addc_u32 s19, s19, 0
	s_mov_b64 vcc, s[6:7]
	v_cndmask_b32_dpp v68, v4, v0, vcc row_ror:8 row_mask:0xf bank_mask:0xf
	v_cndmask_b32_dpp v69, v5, v1, vcc row_ror:8 row_mask:0xf bank_mask:0xf
	v_cndmask_b32_dpp v70, v6, v2, vcc row_ror:8 row_mask:0xf bank_mask:0xf
	v_cndmask_b32_dpp v71, v7, v3, vcc row_ror:8 row_mask:0xf bank_mask:0xf
	s_not_b64 vcc, s[6:7]
	v_cndmask_b32_dpp v64, v0, v4, vcc row_ror:8 row_mask:0xf bank_mask:0xf
	v_cndmask_b32_dpp v65, v1, v5, vcc row_ror:8 row_mask:0xf bank_mask:0xf
	v_cndmask_b32_dpp v66, v2, v6, vcc row_ror:8 row_mask:0xf bank_mask:0xf
	v_cndmask_b32_dpp v67, v3, v7, vcc row_ror:8 row_mask:0xf bank_mask:0xf
	global_store_dwordx4 v171, v[68:71], s[2:3]
	global_store_dwordx4 v171, v[64:67], s[18:19]
	s_waitcnt vmcnt(10)
	s_mov_b64 vcc, s[6:7]
	v_cndmask_b32_dpp v0, v242, v238, vcc row_ror:8 row_mask:0xf bank_mask:0xf
	v_cndmask_b32_dpp v1, v243, v239, vcc row_ror:8 row_mask:0xf bank_mask:0xf
	v_cndmask_b32_dpp v2, v244, v240, vcc row_ror:8 row_mask:0xf bank_mask:0xf
	v_cndmask_b32_dpp v3, v245, v241, vcc row_ror:8 row_mask:0xf bank_mask:0xf
	s_not_b64 vcc, s[6:7]
	v_cndmask_b32_dpp v4, v238, v242, vcc row_ror:8 row_mask:0xf bank_mask:0xf
	v_cndmask_b32_dpp v5, v239, v243, vcc row_ror:8 row_mask:0xf bank_mask:0xf
	v_cndmask_b32_dpp v6, v240, v244, vcc row_ror:8 row_mask:0xf bank_mask:0xf
	v_cndmask_b32_dpp v7, v241, v245, vcc row_ror:8 row_mask:0xf bank_mask:0xf
	v_lshlrev_b32_e32 v246, 16, v0
	v_and_b32_e32 v247, 0xffff0000, v0
	v_pk_fma_f32 v[52:53], v[52:53], v[142:143], v[246:247]
	v_lshlrev_b32_e32 v248, 16, v1
	v_and_b32_e32 v249, 0xffff0000, v1
	v_pk_fma_f32 v[54:55], v[54:55], v[144:145], v[248:249]
	v_lshlrev_b32_e32 v250, 16, v2
	v_and_b32_e32 v251, 0xffff0000, v2
	v_pk_fma_f32 v[48:49], v[48:49], v[150:151], v[250:251]
	v_lshlrev_b32_e32 v208, 16, v3
	v_and_b32_e32 v209, 0xffff0000, v3
	v_pk_fma_f32 v[50:51], v[50:51], v[152:153], v[208:209]
	v_lshlrev_b32_e32 v246, 16, v4
	v_and_b32_e32 v247, 0xffff0000, v4
	v_pk_fma_f32 v[44:45], v[44:45], v[138:139], v[246:247]
	v_lshlrev_b32_e32 v248, 16, v5
	v_and_b32_e32 v249, 0xffff0000, v5
	v_pk_fma_f32 v[46:47], v[46:47], v[140:141], v[248:249]
	v_lshlrev_b32_e32 v250, 16, v6
	v_and_b32_e32 v251, 0xffff0000, v6
	v_pk_fma_f32 v[40:41], v[40:41], v[146:147], v[250:251]
	v_lshlrev_b32_e32 v208, 16, v7
	v_and_b32_e32 v209, 0xffff0000, v7
	v_pk_fma_f32 v[42:43], v[42:43], v[148:149], v[208:209]
	v_cvt_pk_bf16_f32 v0, v52, v53
	v_cvt_pk_bf16_f32 v1, v54, v55
	v_cvt_pk_bf16_f32 v2, v48, v49
	v_cvt_pk_bf16_f32 v3, v50, v51
	v_cvt_pk_bf16_f32 v4, v44, v45
	v_cvt_pk_bf16_f32 v5, v46, v47
	v_cvt_pk_bf16_f32 v6, v40, v41
	v_cvt_pk_bf16_f32 v7, v42, v43
	v_mul_f32_e32 v246, v53, v53
	v_mul_f32_e32 v248, v55, v55
	v_fmac_f32_e32 v246, v52, v52
	v_fmac_f32_e32 v248, v54, v54
	v_add_f32_e32 v246, v246, v248
	v_mul_f32_e32 v248, v49, v49
	v_fmac_f32_e32 v248, v48, v48
	v_add_f32_e32 v246, v246, v248
	v_mul_f32_e32 v248, v51, v51
	v_fmac_f32_e32 v248, v50, v50
	v_add_f32_e32 v246, v248, v246
	v_mul_f32_e32 v247, v45, v45
	v_mul_f32_e32 v248, v47, v47
	v_fmac_f32_e32 v247, v44, v44
	v_fmac_f32_e32 v248, v46, v46
	v_add_f32_e32 v247, v247, v248
	v_mul_f32_e32 v248, v41, v41
	v_fmac_f32_e32 v248, v40, v40
	v_add_f32_e32 v247, v247, v248
	v_mul_f32_e32 v248, v43, v43
	v_fmac_f32_e32 v248, v42, v42
	v_add_f32_e32 v247, v248, v247
	v_add_f32_e32 v246, v246, v247
	v_mov_b32_e32 v247, v246
	s_nop 1
	v_permlane16_swap_b32_e32 v246, v247
	s_nop 1
	v_add_f32_e32 v246, v246, v247
	v_mov_b32_e32 v247, v246
	s_nop 1
	v_permlane32_swap_b32_e32 v246, v247
	v_add_u32_e32 v248, s8, v223
	s_nop 0
	v_add_f32_e32 v246, v246, v247
	s_mov_b64 exec, s[44:45]
	ds_write_b32 v248, v246 offset:2304
	s_mov_b64 exec, -1
	s_add_u32 s2, s2, 0x8000
	s_addc_u32 s3, s3, 0
	s_add_u32 s18, s18, 0x8000
	s_addc_u32 s19, s19, 0
	s_mov_b64 vcc, s[6:7]
	v_cndmask_b32_dpp v52, v4, v0, vcc row_ror:8 row_mask:0xf bank_mask:0xf
	v_cndmask_b32_dpp v53, v5, v1, vcc row_ror:8 row_mask:0xf bank_mask:0xf
	v_cndmask_b32_dpp v54, v6, v2, vcc row_ror:8 row_mask:0xf bank_mask:0xf
	v_cndmask_b32_dpp v55, v7, v3, vcc row_ror:8 row_mask:0xf bank_mask:0xf
	s_not_b64 vcc, s[6:7]
	v_cndmask_b32_dpp v48, v0, v4, vcc row_ror:8 row_mask:0xf bank_mask:0xf
	v_cndmask_b32_dpp v49, v1, v5, vcc row_ror:8 row_mask:0xf bank_mask:0xf
	v_cndmask_b32_dpp v50, v2, v6, vcc row_ror:8 row_mask:0xf bank_mask:0xf
	v_cndmask_b32_dpp v51, v3, v7, vcc row_ror:8 row_mask:0xf bank_mask:0xf
	global_store_dwordx4 v171, v[52:55], s[2:3]
	global_store_dwordx4 v171, v[48:51], s[18:19]
	s_waitcnt vmcnt(8)
	s_mov_b64 vcc, s[6:7]
	v_cndmask_b32_dpp v0, v200, v196, vcc row_ror:8 row_mask:0xf bank_mask:0xf
	v_cndmask_b32_dpp v1, v201, v197, vcc row_ror:8 row_mask:0xf bank_mask:0xf
	v_cndmask_b32_dpp v2, v202, v198, vcc row_ror:8 row_mask:0xf bank_mask:0xf
	v_cndmask_b32_dpp v3, v203, v199, vcc row_ror:8 row_mask:0xf bank_mask:0xf
	s_not_b64 vcc, s[6:7]
	v_cndmask_b32_dpp v4, v196, v200, vcc row_ror:8 row_mask:0xf bank_mask:0xf
	v_cndmask_b32_dpp v5, v197, v201, vcc row_ror:8 row_mask:0xf bank_mask:0xf
	v_cndmask_b32_dpp v6, v198, v202, vcc row_ror:8 row_mask:0xf bank_mask:0xf
	v_cndmask_b32_dpp v7, v199, v203, vcc row_ror:8 row_mask:0xf bank_mask:0xf
	v_lshlrev_b32_e32 v246, 16, v0
	v_and_b32_e32 v247, 0xffff0000, v0
	v_pk_fma_f32 v[36:37], v[36:37], v[142:143], v[246:247]
	v_lshlrev_b32_e32 v248, 16, v1
	v_and_b32_e32 v249, 0xffff0000, v1
	v_pk_fma_f32 v[38:39], v[38:39], v[144:145], v[248:249]
	v_lshlrev_b32_e32 v250, 16, v2
	v_and_b32_e32 v251, 0xffff0000, v2
	v_pk_fma_f32 v[32:33], v[32:33], v[150:151], v[250:251]
	v_lshlrev_b32_e32 v208, 16, v3
	v_and_b32_e32 v209, 0xffff0000, v3
	v_pk_fma_f32 v[34:35], v[34:35], v[152:153], v[208:209]
	v_lshlrev_b32_e32 v246, 16, v4
	v_and_b32_e32 v247, 0xffff0000, v4
	v_pk_fma_f32 v[28:29], v[28:29], v[138:139], v[246:247]
	v_lshlrev_b32_e32 v248, 16, v5
	v_and_b32_e32 v249, 0xffff0000, v5
	v_pk_fma_f32 v[30:31], v[30:31], v[140:141], v[248:249]
	v_lshlrev_b32_e32 v250, 16, v6
	v_and_b32_e32 v251, 0xffff0000, v6
	v_pk_fma_f32 v[24:25], v[24:25], v[146:147], v[250:251]
	v_lshlrev_b32_e32 v208, 16, v7
	v_and_b32_e32 v209, 0xffff0000, v7
	v_pk_fma_f32 v[26:27], v[26:27], v[148:149], v[208:209]
	v_cvt_pk_bf16_f32 v0, v36, v37
	v_cvt_pk_bf16_f32 v1, v38, v39
	v_cvt_pk_bf16_f32 v2, v32, v33
	v_cvt_pk_bf16_f32 v3, v34, v35
	v_cvt_pk_bf16_f32 v4, v28, v29
	v_cvt_pk_bf16_f32 v5, v30, v31
	v_cvt_pk_bf16_f32 v6, v24, v25
	v_cvt_pk_bf16_f32 v7, v26, v27
	v_mul_f32_e32 v246, v37, v37
	v_mul_f32_e32 v248, v39, v39
	v_fmac_f32_e32 v246, v36, v36
	v_fmac_f32_e32 v248, v38, v38
	v_add_f32_e32 v246, v246, v248
	v_mul_f32_e32 v248, v33, v33
	v_fmac_f32_e32 v248, v32, v32
	v_add_f32_e32 v246, v246, v248
	v_mul_f32_e32 v248, v35, v35
	v_fmac_f32_e32 v248, v34, v34
	v_add_f32_e32 v246, v248, v246
	v_mul_f32_e32 v247, v29, v29
	v_mul_f32_e32 v248, v31, v31
	v_fmac_f32_e32 v247, v28, v28
	v_fmac_f32_e32 v248, v30, v30
	v_add_f32_e32 v247, v247, v248
	v_mul_f32_e32 v248, v25, v25
	v_fmac_f32_e32 v248, v24, v24
	v_add_f32_e32 v247, v247, v248
	v_mul_f32_e32 v248, v27, v27
	v_fmac_f32_e32 v248, v26, v26
	v_add_f32_e32 v247, v248, v247
	v_add_f32_e32 v246, v246, v247
	v_mov_b32_e32 v247, v246
	s_nop 1
	v_permlane16_swap_b32_e32 v246, v247
	s_nop 1
	v_add_f32_e32 v246, v246, v247
	v_mov_b32_e32 v247, v246
	s_nop 1
	v_permlane32_swap_b32_e32 v246, v247
	v_add_u32_e32 v248, s8, v223
	s_nop 0
	v_add_f32_e32 v246, v246, v247
	s_mov_b64 exec, s[44:45]
	ds_write_b32 v248, v246 offset:2560
	s_mov_b64 exec, -1
	s_add_u32 s2, s2, 0x8000
	s_addc_u32 s3, s3, 0
	s_add_u32 s18, s18, 0x8000
	s_addc_u32 s19, s19, 0
	s_mov_b64 vcc, s[6:7]
	v_cndmask_b32_dpp v36, v4, v0, vcc row_ror:8 row_mask:0xf bank_mask:0xf
	v_cndmask_b32_dpp v37, v5, v1, vcc row_ror:8 row_mask:0xf bank_mask:0xf
	v_cndmask_b32_dpp v38, v6, v2, vcc row_ror:8 row_mask:0xf bank_mask:0xf
	v_cndmask_b32_dpp v39, v7, v3, vcc row_ror:8 row_mask:0xf bank_mask:0xf
	s_not_b64 vcc, s[6:7]
	v_cndmask_b32_dpp v32, v0, v4, vcc row_ror:8 row_mask:0xf bank_mask:0xf
	v_cndmask_b32_dpp v33, v1, v5, vcc row_ror:8 row_mask:0xf bank_mask:0xf
	v_cndmask_b32_dpp v34, v2, v6, vcc row_ror:8 row_mask:0xf bank_mask:0xf
	v_cndmask_b32_dpp v35, v3, v7, vcc row_ror:8 row_mask:0xf bank_mask:0xf
	global_store_dwordx4 v171, v[36:39], s[2:3]
	global_store_dwordx4 v171, v[32:35], s[18:19]
	s_waitcnt vmcnt(6)
	s_mov_b64 vcc, s[6:7]
	v_cndmask_b32_dpp v0, v234, v204, vcc row_ror:8 row_mask:0xf bank_mask:0xf
	v_cndmask_b32_dpp v1, v235, v205, vcc row_ror:8 row_mask:0xf bank_mask:0xf
	v_cndmask_b32_dpp v2, v236, v206, vcc row_ror:8 row_mask:0xf bank_mask:0xf
	v_cndmask_b32_dpp v3, v237, v207, vcc row_ror:8 row_mask:0xf bank_mask:0xf
	s_not_b64 vcc, s[6:7]
	v_cndmask_b32_dpp v4, v204, v234, vcc row_ror:8 row_mask:0xf bank_mask:0xf
	v_cndmask_b32_dpp v5, v205, v235, vcc row_ror:8 row_mask:0xf bank_mask:0xf
	v_cndmask_b32_dpp v6, v206, v236, vcc row_ror:8 row_mask:0xf bank_mask:0xf
	v_cndmask_b32_dpp v7, v207, v237, vcc row_ror:8 row_mask:0xf bank_mask:0xf
	v_lshlrev_b32_e32 v246, 16, v0
	v_and_b32_e32 v247, 0xffff0000, v0
	v_pk_fma_f32 v[20:21], v[20:21], v[142:143], v[246:247]
	v_lshlrev_b32_e32 v248, 16, v1
	v_and_b32_e32 v249, 0xffff0000, v1
	v_pk_fma_f32 v[22:23], v[22:23], v[144:145], v[248:249]
	v_lshlrev_b32_e32 v250, 16, v2
	v_and_b32_e32 v251, 0xffff0000, v2
	v_pk_fma_f32 v[16:17], v[16:17], v[150:151], v[250:251]
	v_lshlrev_b32_e32 v208, 16, v3
	v_and_b32_e32 v209, 0xffff0000, v3
	v_pk_fma_f32 v[18:19], v[18:19], v[152:153], v[208:209]
	v_lshlrev_b32_e32 v246, 16, v4
	v_and_b32_e32 v247, 0xffff0000, v4
	v_pk_fma_f32 v[12:13], v[12:13], v[138:139], v[246:247]
	v_lshlrev_b32_e32 v248, 16, v5
	v_and_b32_e32 v249, 0xffff0000, v5
	v_pk_fma_f32 v[14:15], v[14:15], v[140:141], v[248:249]
	v_lshlrev_b32_e32 v250, 16, v6
	v_and_b32_e32 v251, 0xffff0000, v6
	v_pk_fma_f32 v[8:9], v[8:9], v[146:147], v[250:251]
	v_lshlrev_b32_e32 v208, 16, v7
	v_and_b32_e32 v209, 0xffff0000, v7
	v_pk_fma_f32 v[10:11], v[10:11], v[148:149], v[208:209]
	v_cvt_pk_bf16_f32 v0, v20, v21
	v_cvt_pk_bf16_f32 v1, v22, v23
	v_cvt_pk_bf16_f32 v2, v16, v17
	v_cvt_pk_bf16_f32 v3, v18, v19
	v_cvt_pk_bf16_f32 v4, v12, v13
	v_cvt_pk_bf16_f32 v5, v14, v15
	v_cvt_pk_bf16_f32 v6, v8, v9
	v_cvt_pk_bf16_f32 v7, v10, v11
	v_mul_f32_e32 v246, v21, v21
	v_mul_f32_e32 v248, v23, v23
	v_fmac_f32_e32 v246, v20, v20
	v_fmac_f32_e32 v248, v22, v22
	v_add_f32_e32 v246, v246, v248
	v_mul_f32_e32 v248, v17, v17
	v_fmac_f32_e32 v248, v16, v16
	v_add_f32_e32 v246, v246, v248
	v_mul_f32_e32 v248, v19, v19
	v_fmac_f32_e32 v248, v18, v18
	v_add_f32_e32 v246, v248, v246
	v_mul_f32_e32 v247, v13, v13
	v_mul_f32_e32 v248, v15, v15
	v_fmac_f32_e32 v247, v12, v12
	v_fmac_f32_e32 v248, v14, v14
	v_add_f32_e32 v247, v247, v248
	v_mul_f32_e32 v248, v9, v9
	v_fmac_f32_e32 v248, v8, v8
	v_add_f32_e32 v247, v247, v248
	v_mul_f32_e32 v248, v11, v11
	v_fmac_f32_e32 v248, v10, v10
	v_add_f32_e32 v247, v248, v247
	v_add_f32_e32 v246, v246, v247
	v_mov_b32_e32 v247, v246
	s_nop 1
	v_permlane16_swap_b32_e32 v246, v247
	s_nop 1
	v_add_f32_e32 v246, v246, v247
	v_mov_b32_e32 v247, v246
	s_nop 1
	v_permlane32_swap_b32_e32 v246, v247
	v_add_u32_e32 v248, s8, v223
	s_nop 0
	v_add_f32_e32 v246, v246, v247
	s_mov_b64 exec, s[44:45]
	ds_write_b32 v248, v246 offset:2816
	s_mov_b64 exec, -1
	s_add_u32 s2, s2, 0x8000
	s_addc_u32 s3, s3, 0
	s_add_u32 s18, s18, 0x8000
	s_addc_u32 s19, s19, 0
	s_mov_b64 vcc, s[6:7]
	v_cndmask_b32_dpp v20, v4, v0, vcc row_ror:8 row_mask:0xf bank_mask:0xf
	v_cndmask_b32_dpp v21, v5, v1, vcc row_ror:8 row_mask:0xf bank_mask:0xf
	v_cndmask_b32_dpp v22, v6, v2, vcc row_ror:8 row_mask:0xf bank_mask:0xf
	v_cndmask_b32_dpp v23, v7, v3, vcc row_ror:8 row_mask:0xf bank_mask:0xf
	s_not_b64 vcc, s[6:7]
	v_cndmask_b32_dpp v16, v0, v4, vcc row_ror:8 row_mask:0xf bank_mask:0xf
	v_cndmask_b32_dpp v17, v1, v5, vcc row_ror:8 row_mask:0xf bank_mask:0xf
	v_cndmask_b32_dpp v18, v2, v6, vcc row_ror:8 row_mask:0xf bank_mask:0xf
	v_cndmask_b32_dpp v19, v3, v7, vcc row_ror:8 row_mask:0xf bank_mask:0xf
	global_store_dwordx4 v171, v[20:23], s[2:3]
	global_store_dwordx4 v171, v[16:19], s[18:19]
	s_branch .LBB0_714
